# prio3 scheme plus last DMA issues of each load segment moved into the MFMA burst
# baseline (speedup 1.0000x reference)
; #define PG8_STAGE(bufoff, gbase, voff) do { _Pragma("unroll") for (int _i = 0; _i < 2; ++_i) \
;         __builtin_amdgcn_global_load_lds((const unsigned*)((const char*)(gbase) + (voff)[_i]), (PG8_LAS unsigned*)(lds + (bufoff) + ldsw + _i * 8192), 16, 0, 0); } while (0)
; #define PG8_LDA(dst, b, h) do { _Pragma("unroll") for (int m = 0; m < 4; ++m) _Pragma("unroll") for (int k = 0; k < 2; ++k) dst[m][k] = *(const PG8_LAS bf16x8*)(lds + PG8_SA(b, h) + aoff + m * 2048 + k * 1024); } while (0)
; #define PG8_LDB(dst, b, h) do { _Pragma("unroll") for (int n = 0; n < 2; ++n) _Pragma("unroll") for (int k = 0; k < 2; ++k) dst[n][k] = *(const PG8_LAS bf16x8*)(lds + PG8_SB(b, h) + boff + n * 2048 + k * 1024); } while (0)
; #define PG8_MMA(ai, bj, At, Bt) do { __builtin_amdgcn_s_setprio(1); _Pragma("unroll") for (int m = 0; m < 4; ++m) _Pragma("unroll") for (int n = 0; n < 2; ++n) _Pragma("unroll") for (int k = 0; k < 2; ++k) \
;         acc[ai][bj][m][n] = __builtin_amdgcn_mfma_f32_16x16x32_bf16(Bt[n][k], At[m][k], acc[ai][bj][m][n], 0, 0, 0); __builtin_amdgcn_s_setprio(0); } while (0)
; #define PG8_WAIT_V(n) asm volatile("s_waitcnt vmcnt(" #n ")" ::: "memory")
; #define PG8_WAIT_L(n) asm volatile("s_waitcnt lgkmcnt(" #n ")" ::: "memory")
; template <class Epi, class Sched, bool ALIGN_EPI = false, bool SP2 = false>
; __device__ __forceinline__ void gemm_phase(PG8_LAS unsigned char* lds, const Gemm g, const Sched& S, const Epi& E) {
;     ...
;             const bool last = (t == nt - 2);
;             const char* a1 = cA + (size_t)(t + 1) * kstep;
;             const char* a2 = last ? nA : cA + (size_t)(t + 2) * kstep; const char* b2 = last ? nB : cB + (size_t)(t + 2) * kstep;
;             const char* a3 = a2 + kstep; const char* b3 = b2 + kstep;
;             if (last && has_next) S.a_ready(nxt);
;             if constexpr (SP2) {
;             PG8_LDB(B0, 0, 0); PG8_LDB(B1, 0, 1); PG8_SCHED; PG8_LDA(At, 0, 0); PG8_STAGE(PG8_SA(1, 1), a1 + hstep, voffA);
;             PG8_WAIT_V(8); PG8_WAIT_L(0); PG8_BAR; PG8_MMA(0, 0, At, B0); PG8_MMA(0, 1, At, B1); PG8_BAR; PG8_SCHED;
;             PG8_LDA(At, 0, 1); PG8_STAGE(PG8_SB(0, 0), b2, voffB); PG8_STAGE(PG8_SB(0, 1), b2 + hstep, voffB); PG8_STAGE(PG8_SA(0, 0), a2, voffA);
;             PG8_WAIT_V(8); PG8_WAIT_L(0); PG8_BAR; PG8_MMA(1, 0, At, B0); PG8_MMA(1, 1, At, B1); PG8_BAR; PG8_SCHED;
.LBB0_301:
	s_add_u32 s38, s36, 0xfff80080
	s_addc_u32 s39, s37, -1
	s_add_i32 s61, 0, 0x10000
	s_cmp_eq_u32 s60, 28
	s_cselect_b32 s41, s11, s39
	s_cselect_b32 s40, s13, s38
	s_cselect_b32 s39, s56, s59
	s_cselect_b32 s38, s57, s58
	s_add_i32 s64, 0, 0x14000
	v_add_u32_e32 v158, s61, v150
	v_add_u32_e32 v162, s64, v150
	ds_read_b128 v[142:145], v158
	ds_read_b128 v[146:149], v158 offset:1024
	ds_read_b128 v[154:157], v158 offset:2048
	ds_read_b128 v[158:161], v158 offset:3072
	ds_read_b128 v[174:177], v162
	ds_read_b128 v[178:181], v162 offset:1024
	ds_read_b128 v[204:207], v162 offset:2048
	ds_read_b128 v[208:211], v162 offset:3072
	s_add_i32 m0, s47, 0xc000
	ds_read_b128 v[212:215], v153
	ds_read_b128 v[216:219], v153 offset:1024
	ds_read_b128 v[220:223], v153 offset:2048
	ds_read_b128 v[224:227], v153 offset:3072
	ds_read_b128 v[228:231], v153 offset:4096
	ds_read_b128 v[232:235], v153 offset:5120
	ds_read_b128 v[236:239], v153 offset:6144
	ds_read_b128 v[240:243], v153 offset:7168
	global_load_lds_dwordx4 v138, s[36:37]
	s_nop 0
	s_waitcnt vmcnt(7)
	s_waitcnt lgkmcnt(0)
	s_barrier
	s_setprio 0
	s_waitcnt lgkmcnt(0)
	v_mfma_f32_16x16x32_bf16 v[128:131], v[142:145], v[212:215], v[128:131]
	v_mfma_f32_16x16x32_bf16 v[120:123], v[154:157], v[212:215], v[120:123]
	v_mfma_f32_16x16x32_bf16 v[112:115], v[142:145], v[220:223], v[112:115]
	s_add_i32 m0, s47, 0xe000
	v_mfma_f32_16x16x32_bf16 v[104:107], v[154:157], v[220:223], v[104:107]
	global_load_lds_dwordx4 v140, s[36:37]
	v_mfma_f32_16x16x32_bf16 v[96:99], v[142:145], v[228:231], v[96:99]
	v_mfma_f32_16x16x32_bf16 v[88:91], v[154:157], v[228:231], v[88:91]
	v_mfma_f32_16x16x32_bf16 v[80:83], v[142:145], v[236:239], v[80:83]
	v_mfma_f32_16x16x32_bf16 v[72:75], v[154:157], v[236:239], v[72:75]
	v_mfma_f32_16x16x32_bf16 v[128:131], v[146:149], v[216:219], v[128:131]
	v_mfma_f32_16x16x32_bf16 v[120:123], v[158:161], v[216:219], v[120:123]
	v_mfma_f32_16x16x32_bf16 v[112:115], v[146:149], v[224:227], v[112:115]
	v_mfma_f32_16x16x32_bf16 v[104:107], v[158:161], v[224:227], v[104:107]
	v_mfma_f32_16x16x32_bf16 v[96:99], v[146:149], v[232:235], v[96:99]
	v_mfma_f32_16x16x32_bf16 v[88:91], v[158:161], v[232:235], v[88:91]
	v_mfma_f32_16x16x32_bf16 v[80:83], v[146:149], v[240:243], v[80:83]
	v_mfma_f32_16x16x32_bf16 v[72:75], v[158:161], v[240:243], v[72:75]
	v_mfma_f32_16x16x32_bf16 v[124:127], v[174:177], v[212:215], v[124:127]
	v_mfma_f32_16x16x32_bf16 v[116:119], v[204:207], v[212:215], v[116:119]
	v_mfma_f32_16x16x32_bf16 v[108:111], v[174:177], v[220:223], v[108:111]
	v_mfma_f32_16x16x32_bf16 v[100:103], v[204:207], v[220:223], v[100:103]
	v_mfma_f32_16x16x32_bf16 v[92:95], v[174:177], v[228:231], v[92:95]
	v_mfma_f32_16x16x32_bf16 v[84:87], v[204:207], v[228:231], v[84:87]
	v_mfma_f32_16x16x32_bf16 v[76:79], v[174:177], v[236:239], v[76:79]
	v_mfma_f32_16x16x32_bf16 v[68:71], v[204:207], v[236:239], v[68:71]
	v_mfma_f32_16x16x32_bf16 v[124:127], v[178:181], v[216:219], v[124:127]
	v_mfma_f32_16x16x32_bf16 v[116:119], v[208:211], v[216:219], v[116:119]
	v_mfma_f32_16x16x32_bf16 v[108:111], v[178:181], v[224:227], v[108:111]
	v_mfma_f32_16x16x32_bf16 v[100:103], v[208:211], v[224:227], v[100:103]
	v_mfma_f32_16x16x32_bf16 v[92:95], v[178:181], v[232:235], v[92:95]
	v_mfma_f32_16x16x32_bf16 v[84:87], v[208:211], v[232:235], v[84:87]
	v_mfma_f32_16x16x32_bf16 v[76:79], v[178:181], v[240:243], v[76:79]
	v_mfma_f32_16x16x32_bf16 v[68:71], v[208:211], v[240:243], v[68:71]
	s_setprio 3
	s_barrier
	s_add_i32 s61, s61, s42
	s_mov_b32 m0, s61
	ds_read_b128 v[212:215], v153 offset:16384
	ds_read_b128 v[216:219], v153 offset:17408
	ds_read_b128 v[220:223], v153 offset:18432
	ds_read_b128 v[224:227], v153 offset:19456
	ds_read_b128 v[228:231], v153 offset:20480
	ds_read_b128 v[232:235], v153 offset:21504
	ds_read_b128 v[236:239], v153 offset:22528
	ds_read_b128 v[240:243], v153 offset:23552
	global_load_lds_dwordx4 v2, s[38:39]
	s_add_i32 m0, s61, 0x2000
	s_add_u32 s62, s38, 0x80000
	s_addc_u32 s63, s39, 0
	s_add_i32 s61, s64, s42
	global_load_lds_dwordx4 v132, s[38:39]
	s_mov_b32 m0, s61
	s_nop 0
	global_load_lds_dwordx4 v2, s[62:63]
	s_add_i32 m0, s61, 0x2000
	s_nop 0
	global_load_lds_dwordx4 v132, s[62:63]
	s_nop 0
	s_nop 0
	s_nop 0
	s_nop 0
	s_nop 0
	s_nop 0
	s_nop 0
	s_waitcnt vmcnt(6)
	s_waitcnt lgkmcnt(0)
	s_barrier
	s_setprio 0
	s_waitcnt lgkmcnt(0)
	v_mfma_f32_16x16x32_bf16 v[64:67], v[142:145], v[212:215], v[64:67]
	v_mfma_f32_16x16x32_bf16 v[56:59], v[154:157], v[212:215], v[56:59]
	v_mfma_f32_16x16x32_bf16 v[48:51], v[142:145], v[220:223], v[48:51]
	s_mov_b32 m0, s47
	v_mfma_f32_16x16x32_bf16 v[40:43], v[154:157], v[220:223], v[40:43]
	global_load_lds_dwordx4 v136, s[40:41]
	v_mfma_f32_16x16x32_bf16 v[32:35], v[142:145], v[228:231], v[32:35]
	v_mfma_f32_16x16x32_bf16 v[24:27], v[154:157], v[228:231], v[24:27]
	v_mfma_f32_16x16x32_bf16 v[16:19], v[142:145], v[236:239], v[16:19]
	v_mfma_f32_16x16x32_bf16 v[8:11], v[154:157], v[236:239], v[8:11]
	v_mfma_f32_16x16x32_bf16 v[64:67], v[146:149], v[216:219], v[64:67]
	v_mfma_f32_16x16x32_bf16 v[56:59], v[158:161], v[216:219], v[56:59]
	v_mfma_f32_16x16x32_bf16 v[48:51], v[146:149], v[224:227], v[48:51]
	s_mov_b32 m0, s48
	v_mfma_f32_16x16x32_bf16 v[40:43], v[158:161], v[224:227], v[40:43]
	global_load_lds_dwordx4 v134, s[40:41]
	v_mfma_f32_16x16x32_bf16 v[32:35], v[146:149], v[232:235], v[32:35]
	v_mfma_f32_16x16x32_bf16 v[24:27], v[158:161], v[232:235], v[24:27]
	v_mfma_f32_16x16x32_bf16 v[16:19], v[146:149], v[240:243], v[16:19]
	v_mfma_f32_16x16x32_bf16 v[8:11], v[158:161], v[240:243], v[8:11]
	v_mfma_f32_16x16x32_bf16 v[60:63], v[174:177], v[212:215], v[60:63]
	v_mfma_f32_16x16x32_bf16 v[52:55], v[204:207], v[212:215], v[52:55]
	v_mfma_f32_16x16x32_bf16 v[44:47], v[174:177], v[220:223], v[44:47]
	v_mfma_f32_16x16x32_bf16 v[36:39], v[204:207], v[220:223], v[36:39]
	v_mfma_f32_16x16x32_bf16 v[28:31], v[174:177], v[228:231], v[28:31]
	v_mfma_f32_16x16x32_bf16 v[20:23], v[204:207], v[228:231], v[20:23]
	v_mfma_f32_16x16x32_bf16 v[12:15], v[174:177], v[236:239], v[12:15]
	v_mfma_f32_16x16x32_bf16 v[4:7], v[204:207], v[236:239], v[4:7]
	v_mfma_f32_16x16x32_bf16 v[60:63], v[178:181], v[216:219], v[60:63]
	v_mfma_f32_16x16x32_bf16 v[52:55], v[208:211], v[216:219], v[52:55]
	v_mfma_f32_16x16x32_bf16 v[44:47], v[178:181], v[224:227], v[44:47]
	v_mfma_f32_16x16x32_bf16 v[36:39], v[208:211], v[224:227], v[36:39]
	v_mfma_f32_16x16x32_bf16 v[28:31], v[178:181], v[232:235], v[28:31]
	v_mfma_f32_16x16x32_bf16 v[20:23], v[208:211], v[232:235], v[20:23]
	v_mfma_f32_16x16x32_bf16 v[12:15], v[178:181], v[240:243], v[12:15]
	v_mfma_f32_16x16x32_bf16 v[4:7], v[208:211], v[240:243], v[4:7]
	s_setprio 3
	s_barrier
; #define PG8_STAGE(bufoff, gbase, voff) do { _Pragma("unroll") for (int _i = 0; _i < 2; ++_i) \
;         __builtin_amdgcn_global_load_lds((const unsigned*)((const char*)(gbase) + (voff)[_i]), (PG8_LAS unsigned*)(lds + (bufoff) + ldsw + _i * 8192), 16, 0, 0); } while (0)
; #define PG8_LDA(dst, b, h) do { _Pragma("unroll") for (int m = 0; m < 4; ++m) _Pragma("unroll") for (int k = 0; k < 2; ++k) dst[m][k] = *(const PG8_LAS bf16x8*)(lds + PG8_SA(b, h) + aoff + m * 2048 + k * 1024); } while (0)
; #define PG8_LDB(dst, b, h) do { _Pragma("unroll") for (int n = 0; n < 2; ++n) _Pragma("unroll") for (int k = 0; k < 2; ++k) dst[n][k] = *(const PG8_LAS bf16x8*)(lds + PG8_SB(b, h) + boff + n * 2048 + k * 1024); } while (0)
; #define PG8_MMA(ai, bj, At, Bt) do { __builtin_amdgcn_s_setprio(1); _Pragma("unroll") for (int m = 0; m < 4; ++m) _Pragma("unroll") for (int n = 0; n < 2; ++n) _Pragma("unroll") for (int k = 0; k < 2; ++k) \
;         acc[ai][bj][m][n] = __builtin_amdgcn_mfma_f32_16x16x32_bf16(Bt[n][k], At[m][k], acc[ai][bj][m][n], 0, 0, 0); __builtin_amdgcn_s_setprio(0); } while (0)
; #define PG8_WAIT_V(n) asm volatile("s_waitcnt vmcnt(" #n ")" ::: "memory")
; #define PG8_WAIT_L(n) asm volatile("s_waitcnt lgkmcnt(" #n ")" ::: "memory")
; #define PG8_BAR __builtin_amdgcn_s_barrier()
; #define PG8_SCHED __builtin_amdgcn_sched_barrier(0)
; template <class Epi, class Sched, bool ALIGN_EPI = false, bool SP2 = false>
; __device__ __forceinline__ void gemm_phase(PG8_LAS unsigned char* lds, const Gemm g, const Sched& S, const Epi& E) {
;     ...
;             PG8_LDB(B0, 1, 0); PG8_LDB(B1, 1, 1); PG8_SCHED; PG8_LDA(At, 1, 0); PG8_STAGE(PG8_SA(0, 1), a2 + hstep, voffA);
;             PG8_WAIT_V(8); PG8_WAIT_L(0); PG8_BAR; PG8_MMA(0, 0, At, B0); PG8_MMA(0, 1, At, B1); PG8_BAR; PG8_SCHED;
;             PG8_LDA(At, 1, 1); PG8_STAGE(PG8_SB(1, 0), b3, voffB); PG8_STAGE(PG8_SB(1, 1), b3 + hstep, voffB); PG8_STAGE(PG8_SA(1, 0), a3, voffA);
;             PG8_WAIT_V(8); PG8_WAIT_L(0); PG8_BAR; PG8_MMA(1, 0, At, B0); PG8_MMA(1, 1, At, B1); PG8_BAR; PG8_SCHED;
	s_add_i32 s61, 0, 0x18000
	s_add_i32 s62, 0, 0x1c000
	v_add_u32_e32 v158, s61, v150
	v_add_u32_e32 v164, s62, v150
	ds_read_b128 v[142:145], v158
	ds_read_b128 v[146:149], v158 offset:1024
	ds_read_b128 v[154:157], v158 offset:2048
	ds_read_b128 v[158:161], v158 offset:3072
	ds_read_b128 v[174:177], v164
	ds_read_b128 v[178:181], v164 offset:1024
	ds_read_b128 v[204:207], v164 offset:2048
	ds_read_b128 v[208:211], v164 offset:3072
	s_add_u32 s100, s40, 0x80
	s_addc_u32 s101, s41, 0
	s_add_u32 s40, s40, 0x80000
	s_addc_u32 s41, s41, 0
	s_mov_b32 m0, s49
	ds_read_b128 v[212:215], v153 offset:32768
	ds_read_b128 v[216:219], v153 offset:33792
	ds_read_b128 v[220:223], v153 offset:34816
	ds_read_b128 v[224:227], v153 offset:35840
	ds_read_b128 v[228:231], v153 offset:36864
	ds_read_b128 v[232:235], v153 offset:37888
	ds_read_b128 v[236:239], v153 offset:38912
	ds_read_b128 v[240:243], v153 offset:39936
	global_load_lds_dwordx4 v136, s[40:41]
	s_waitcnt vmcnt(7)
	s_waitcnt lgkmcnt(0)
	s_barrier
	s_setprio 0
	s_waitcnt lgkmcnt(0)
	v_mfma_f32_16x16x32_bf16 v[128:131], v[142:145], v[212:215], v[128:131]
	v_mfma_f32_16x16x32_bf16 v[120:123], v[154:157], v[212:215], v[120:123]
	v_mfma_f32_16x16x32_bf16 v[112:115], v[142:145], v[220:223], v[112:115]
	s_mov_b32 m0, s50
	v_mfma_f32_16x16x32_bf16 v[104:107], v[154:157], v[220:223], v[104:107]
	global_load_lds_dwordx4 v134, s[40:41]
	v_mfma_f32_16x16x32_bf16 v[96:99], v[142:145], v[228:231], v[96:99]
	v_mfma_f32_16x16x32_bf16 v[88:91], v[154:157], v[228:231], v[88:91]
	v_mfma_f32_16x16x32_bf16 v[80:83], v[142:145], v[236:239], v[80:83]
	v_mfma_f32_16x16x32_bf16 v[72:75], v[154:157], v[236:239], v[72:75]
	v_mfma_f32_16x16x32_bf16 v[128:131], v[146:149], v[216:219], v[128:131]
	v_mfma_f32_16x16x32_bf16 v[120:123], v[158:161], v[216:219], v[120:123]
	v_mfma_f32_16x16x32_bf16 v[112:115], v[146:149], v[224:227], v[112:115]
	v_mfma_f32_16x16x32_bf16 v[104:107], v[158:161], v[224:227], v[104:107]
	v_mfma_f32_16x16x32_bf16 v[96:99], v[146:149], v[232:235], v[96:99]
	v_mfma_f32_16x16x32_bf16 v[88:91], v[158:161], v[232:235], v[88:91]
	v_mfma_f32_16x16x32_bf16 v[80:83], v[146:149], v[240:243], v[80:83]
	v_mfma_f32_16x16x32_bf16 v[72:75], v[158:161], v[240:243], v[72:75]
	v_mfma_f32_16x16x32_bf16 v[124:127], v[174:177], v[212:215], v[124:127]
	v_mfma_f32_16x16x32_bf16 v[116:119], v[204:207], v[212:215], v[116:119]
	v_mfma_f32_16x16x32_bf16 v[108:111], v[174:177], v[220:223], v[108:111]
	v_mfma_f32_16x16x32_bf16 v[100:103], v[204:207], v[220:223], v[100:103]
	v_mfma_f32_16x16x32_bf16 v[92:95], v[174:177], v[228:231], v[92:95]
	v_mfma_f32_16x16x32_bf16 v[84:87], v[204:207], v[228:231], v[84:87]
	v_mfma_f32_16x16x32_bf16 v[76:79], v[174:177], v[236:239], v[76:79]
	v_mfma_f32_16x16x32_bf16 v[68:71], v[204:207], v[236:239], v[68:71]
	v_mfma_f32_16x16x32_bf16 v[124:127], v[178:181], v[216:219], v[124:127]
	v_mfma_f32_16x16x32_bf16 v[116:119], v[208:211], v[216:219], v[116:119]
	v_mfma_f32_16x16x32_bf16 v[108:111], v[178:181], v[224:227], v[108:111]
	v_mfma_f32_16x16x32_bf16 v[100:103], v[208:211], v[224:227], v[100:103]
	v_mfma_f32_16x16x32_bf16 v[92:95], v[178:181], v[232:235], v[92:95]
	v_mfma_f32_16x16x32_bf16 v[84:87], v[208:211], v[232:235], v[84:87]
	v_mfma_f32_16x16x32_bf16 v[76:79], v[178:181], v[240:243], v[76:79]
	v_mfma_f32_16x16x32_bf16 v[68:71], v[208:211], v[240:243], v[68:71]
	s_setprio 3
	s_barrier
	s_add_i32 s40, s61, s42
	s_add_i32 m0, s40, 0xffffff80
	ds_read_b128 v[212:215], v153 offset:49152
	ds_read_b128 v[216:219], v153 offset:50176
	ds_read_b128 v[220:223], v153 offset:51200
	ds_read_b128 v[224:227], v153 offset:52224
	ds_read_b128 v[228:231], v153 offset:53248
	ds_read_b128 v[232:235], v153 offset:54272
	ds_read_b128 v[236:239], v153 offset:55296
	ds_read_b128 v[240:243], v153 offset:56320
	global_load_lds_dwordx4 v2, s[38:39] offset:128
	s_add_i32 m0, s40, 0x1f80
	s_add_i32 s40, s62, s42
	global_load_lds_dwordx4 v132, s[38:39] offset:128
	s_add_u32 s38, s38, 0x80080
	s_addc_u32 s39, s39, 0
	s_mov_b32 m0, s40
	s_nop 0
	global_load_lds_dwordx4 v2, s[38:39]
	s_add_i32 m0, s40, 0x2000
	s_nop 0
	global_load_lds_dwordx4 v132, s[38:39]
	s_waitcnt vmcnt(6)
	s_waitcnt lgkmcnt(0)
	s_barrier
	s_setprio 0
	s_waitcnt lgkmcnt(0)
	v_mfma_f32_16x16x32_bf16 v[64:67], v[142:145], v[212:215], v[64:67]
	v_mfma_f32_16x16x32_bf16 v[56:59], v[154:157], v[212:215], v[56:59]
	v_mfma_f32_16x16x32_bf16 v[48:51], v[142:145], v[220:223], v[48:51]
	s_mov_b32 m0, s51
	v_mfma_f32_16x16x32_bf16 v[40:43], v[154:157], v[220:223], v[40:43]
	global_load_lds_dwordx4 v136, s[100:101]
	v_mfma_f32_16x16x32_bf16 v[32:35], v[142:145], v[228:231], v[32:35]
	v_mfma_f32_16x16x32_bf16 v[24:27], v[154:157], v[228:231], v[24:27]
	v_mfma_f32_16x16x32_bf16 v[16:19], v[142:145], v[236:239], v[16:19]
	v_mfma_f32_16x16x32_bf16 v[8:11], v[154:157], v[236:239], v[8:11]
	v_mfma_f32_16x16x32_bf16 v[64:67], v[146:149], v[216:219], v[64:67]
	v_mfma_f32_16x16x32_bf16 v[56:59], v[158:161], v[216:219], v[56:59]
	v_mfma_f32_16x16x32_bf16 v[48:51], v[146:149], v[224:227], v[48:51]
	s_mov_b32 m0, s53
	v_mfma_f32_16x16x32_bf16 v[40:43], v[158:161], v[224:227], v[40:43]
	global_load_lds_dwordx4 v134, s[100:101]
	v_mfma_f32_16x16x32_bf16 v[32:35], v[146:149], v[232:235], v[32:35]
	v_mfma_f32_16x16x32_bf16 v[24:27], v[158:161], v[232:235], v[24:27]
	v_mfma_f32_16x16x32_bf16 v[16:19], v[146:149], v[240:243], v[16:19]
	v_mfma_f32_16x16x32_bf16 v[8:11], v[158:161], v[240:243], v[8:11]
	v_mfma_f32_16x16x32_bf16 v[60:63], v[174:177], v[212:215], v[60:63]
	v_mfma_f32_16x16x32_bf16 v[52:55], v[204:207], v[212:215], v[52:55]
	v_mfma_f32_16x16x32_bf16 v[44:47], v[174:177], v[220:223], v[44:47]
	v_mfma_f32_16x16x32_bf16 v[36:39], v[204:207], v[220:223], v[36:39]
	v_mfma_f32_16x16x32_bf16 v[28:31], v[174:177], v[228:231], v[28:31]
	v_mfma_f32_16x16x32_bf16 v[20:23], v[204:207], v[228:231], v[20:23]
	v_mfma_f32_16x16x32_bf16 v[12:15], v[174:177], v[236:239], v[12:15]
	v_mfma_f32_16x16x32_bf16 v[4:7], v[204:207], v[236:239], v[4:7]
	v_mfma_f32_16x16x32_bf16 v[60:63], v[178:181], v[216:219], v[60:63]
	v_mfma_f32_16x16x32_bf16 v[52:55], v[208:211], v[216:219], v[52:55]
	v_mfma_f32_16x16x32_bf16 v[44:47], v[178:181], v[224:227], v[44:47]
	v_mfma_f32_16x16x32_bf16 v[36:39], v[208:211], v[224:227], v[36:39]
	v_mfma_f32_16x16x32_bf16 v[28:31], v[178:181], v[232:235], v[28:31]
	v_mfma_f32_16x16x32_bf16 v[20:23], v[208:211], v[232:235], v[20:23]
	v_mfma_f32_16x16x32_bf16 v[12:15], v[178:181], v[240:243], v[12:15]
	v_mfma_f32_16x16x32_bf16 v[4:7], v[208:211], v[240:243], v[4:7]
	s_setprio 3
	s_barrier
	s_add_i32 s60, s60, 2
	s_add_u32 s36, s36, 0x100
	s_addc_u32 s37, s37, 0
	s_add_u32 s58, s58, 0x100
	s_addc_u32 s59, s59, 0
	s_cmp_gt_u32 s60, 29
	s_cbranch_scc0 .LBB0_301
	s_and_b64 vcc, exec, s[8:9]
	s_cbranch_vccz .LBB0_304
	s_barrier

; #define PG8_STAGE(bufoff, gbase, voff) do { _Pragma("unroll") for (int _i = 0; _i < 2; ++_i) \
;         __builtin_amdgcn_global_load_lds((const unsigned*)((const char*)(gbase) + (voff)[_i]), (PG8_LAS unsigned*)(lds + (bufoff) + ldsw + _i * 8192), 16, 0, 0); } while (0)
; #define PG8_LDA(dst, b, h) do { _Pragma("unroll") for (int m = 0; m < 4; ++m) _Pragma("unroll") for (int k = 0; k < 2; ++k) dst[m][k] = *(const PG8_LAS bf16x8*)(lds + PG8_SA(b, h) + aoff + m * 2048 + k * 1024); } while (0)
; #define PG8_LDB(dst, b, h) do { _Pragma("unroll") for (int n = 0; n < 2; ++n) _Pragma("unroll") for (int k = 0; k < 2; ++k) dst[n][k] = *(const PG8_LAS bf16x8*)(lds + PG8_SB(b, h) + boff + n * 2048 + k * 1024); } while (0)
; #define PG8_MMA(ai, bj, At, Bt) do { __builtin_amdgcn_s_setprio(1); _Pragma("unroll") for (int m = 0; m < 4; ++m) _Pragma("unroll") for (int n = 0; n < 2; ++n) _Pragma("unroll") for (int k = 0; k < 2; ++k) \
;         acc[ai][bj][m][n] = __builtin_amdgcn_mfma_f32_16x16x32_bf16(Bt[n][k], At[m][k], acc[ai][bj][m][n], 0, 0, 0); __builtin_amdgcn_s_setprio(0); } while (0)
; #define PG8_WAIT_V(n) asm volatile("s_waitcnt vmcnt(" #n ")" ::: "memory")
; #define PG8_WAIT_L(n) asm volatile("s_waitcnt lgkmcnt(" #n ")" ::: "memory")
; template <class Epi, class Sched, bool ALIGN_EPI = false, bool SP2 = false>
; __device__ __forceinline__ void gemm_phase(PG8_LAS unsigned char* lds, const Gemm g, const Sched& S, const Epi& E) {
;     ...
;             const bool last = (t == nt - 2);
;             const char* a1 = cA + (size_t)(t + 1) * kstep;
;             const char* a2 = last ? nA : cA + (size_t)(t + 2) * kstep; const char* b2 = last ? nB : cB + (size_t)(t + 2) * kstep;
;             const char* a3 = a2 + kstep; const char* b3 = b2 + kstep;
;             if (last && has_next) S.a_ready(nxt);
;             if constexpr (SP2) {
;             PG8_LDB(B0, 0, 0); PG8_LDB(B1, 0, 1); PG8_SCHED; PG8_LDA(At, 0, 0); PG8_STAGE(PG8_SA(1, 1), a1 + hstep, voffA);
;             PG8_WAIT_V(8); PG8_WAIT_L(0); PG8_BAR; PG8_MMA(0, 0, At, B0); PG8_MMA(0, 1, At, B1); PG8_BAR; PG8_SCHED;
;             PG8_LDA(At, 0, 1); PG8_STAGE(PG8_SB(0, 0), b2, voffB); PG8_STAGE(PG8_SB(0, 1), b2 + hstep, voffB); PG8_STAGE(PG8_SA(0, 0), a2, voffA);
;             PG8_WAIT_V(8); PG8_WAIT_L(0); PG8_BAR; PG8_MMA(1, 0, At, B0); PG8_MMA(1, 1, At, B1); PG8_BAR; PG8_SCHED;
.LBB0_575:
	s_add_u32 s36, s34, 0x100
	s_addc_u32 s37, s35, 0
	s_add_i32 s64, 0, 0x10000
	s_cmpk_eq_i32 s63, 0x52
	s_cselect_b32 s41, s5, s37
	s_cselect_b32 s40, s4, s36
	v_add_u32_e32 v135, s64, v173
	s_cselect_b32 s39, s31, s62
	s_cselect_b32 s38, s30, s61
	s_add_i32 s65, 0, 0x14000
	ds_read_b128 v[142:145], v135
	ds_read_b128 v[146:149], v135 offset:1024
	ds_read_b128 v[150:153], v135 offset:2048
	ds_read_b128 v[154:157], v135 offset:3072
	v_add_u32_e32 v135, s65, v173
	ds_read_b128 v[158:161], v135
	ds_read_b128 v[174:177], v135 offset:1024
	ds_read_b128 v[180:183], v135 offset:2048
	ds_read_b128 v[204:207], v135 offset:3072
	v_lshl_add_u64 v[162:163], s[34:35], 0, v[138:139]
	s_add_i32 m0, s47, 0xc000
	ds_read_b128 v[208:211], v179
	ds_read_b128 v[212:215], v179 offset:1024
	ds_read_b128 v[216:219], v179 offset:2048
	ds_read_b128 v[220:223], v179 offset:3072
	ds_read_b128 v[224:227], v179 offset:4096
	ds_read_b128 v[228:231], v179 offset:5120
	ds_read_b128 v[232:235], v179 offset:6144
	ds_read_b128 v[236:239], v179 offset:7168
	global_load_lds_dwordx4 v[162:163], off
	v_lshl_add_u64 v[162:163], s[34:35], 0, v[140:141]
	s_nop 0
	s_waitcnt vmcnt(7)
	s_waitcnt lgkmcnt(0)
	s_barrier
	s_setprio 0
	s_waitcnt lgkmcnt(0)
	v_mfma_f32_16x16x32_bf16 v[128:131], v[142:145], v[208:211], v[128:131]
	v_mfma_f32_16x16x32_bf16 v[124:127], v[150:153], v[208:211], v[124:127]
	v_mfma_f32_16x16x32_bf16 v[112:115], v[142:145], v[216:219], v[112:115]
	s_add_i32 m0, s47, 0xe000
	v_mfma_f32_16x16x32_bf16 v[108:111], v[150:153], v[216:219], v[108:111]
	global_load_lds_dwordx4 v[162:163], off
	v_mfma_f32_16x16x32_bf16 v[96:99], v[142:145], v[224:227], v[96:99]
	v_mfma_f32_16x16x32_bf16 v[92:95], v[150:153], v[224:227], v[92:95]
	v_mfma_f32_16x16x32_bf16 v[80:83], v[142:145], v[232:235], v[80:83]
	v_mfma_f32_16x16x32_bf16 v[76:79], v[150:153], v[232:235], v[76:79]
	v_mfma_f32_16x16x32_bf16 v[128:131], v[146:149], v[212:215], v[128:131]
	v_mfma_f32_16x16x32_bf16 v[124:127], v[154:157], v[212:215], v[124:127]
	v_mfma_f32_16x16x32_bf16 v[112:115], v[146:149], v[220:223], v[112:115]
	v_mfma_f32_16x16x32_bf16 v[108:111], v[154:157], v[220:223], v[108:111]
	v_mfma_f32_16x16x32_bf16 v[96:99], v[146:149], v[228:231], v[96:99]
	v_mfma_f32_16x16x32_bf16 v[92:95], v[154:157], v[228:231], v[92:95]
	v_mfma_f32_16x16x32_bf16 v[80:83], v[146:149], v[236:239], v[80:83]
	v_mfma_f32_16x16x32_bf16 v[76:79], v[154:157], v[236:239], v[76:79]
	v_mfma_f32_16x16x32_bf16 v[120:123], v[158:161], v[208:211], v[120:123]
	v_mfma_f32_16x16x32_bf16 v[116:119], v[180:183], v[208:211], v[116:119]
	v_mfma_f32_16x16x32_bf16 v[104:107], v[158:161], v[216:219], v[104:107]
	v_mfma_f32_16x16x32_bf16 v[100:103], v[180:183], v[216:219], v[100:103]
	v_mfma_f32_16x16x32_bf16 v[88:91], v[158:161], v[224:227], v[88:91]
	v_mfma_f32_16x16x32_bf16 v[84:87], v[180:183], v[224:227], v[84:87]
	v_mfma_f32_16x16x32_bf16 v[72:75], v[158:161], v[232:235], v[72:75]
	v_mfma_f32_16x16x32_bf16 v[68:71], v[180:183], v[232:235], v[68:71]
	v_mfma_f32_16x16x32_bf16 v[120:123], v[174:177], v[212:215], v[120:123]
	v_mfma_f32_16x16x32_bf16 v[116:119], v[204:207], v[212:215], v[116:119]
	v_mfma_f32_16x16x32_bf16 v[104:107], v[174:177], v[220:223], v[104:107]
	v_mfma_f32_16x16x32_bf16 v[100:103], v[204:207], v[220:223], v[100:103]
	v_mfma_f32_16x16x32_bf16 v[88:91], v[174:177], v[228:231], v[88:91]
	v_mfma_f32_16x16x32_bf16 v[84:87], v[204:207], v[228:231], v[84:87]
	v_mfma_f32_16x16x32_bf16 v[72:75], v[174:177], v[236:239], v[72:75]
	v_mfma_f32_16x16x32_bf16 v[68:71], v[204:207], v[236:239], v[68:71]
	s_setprio 3
	s_barrier
	s_add_i32 s34, s64, s46
	s_mov_b32 m0, s34
	ds_read_b128 v[208:211], v179 offset:16384
	ds_read_b128 v[212:215], v179 offset:17408
	ds_read_b128 v[216:219], v179 offset:18432
	ds_read_b128 v[220:223], v179 offset:19456
	ds_read_b128 v[224:227], v179 offset:20480
	ds_read_b128 v[228:231], v179 offset:21504
	ds_read_b128 v[232:235], v179 offset:22528
	ds_read_b128 v[236:239], v179 offset:23552
	global_load_lds_dwordx4 v2, s[38:39]
	s_add_i32 m0, s34, 0x2000
	s_add_u32 s34, s38, 0x158000
	s_addc_u32 s35, s39, 0
	s_add_i32 s64, s65, s46
	global_load_lds_dwordx4 v132, s[38:39]
	s_mov_b32 m0, s64
	s_nop 0
	global_load_lds_dwordx4 v2, s[34:35]
	s_add_i32 m0, s64, 0x2000
	s_nop 0
	global_load_lds_dwordx4 v132, s[34:35]
	s_nop 0
	s_nop 0
	s_nop 0
	s_nop 0
	s_nop 0
	s_nop 0
	s_nop 0
	s_waitcnt vmcnt(6)
	s_waitcnt lgkmcnt(0)
	s_barrier
	s_setprio 0
	s_waitcnt lgkmcnt(0)
	v_mfma_f32_16x16x32_bf16 v[64:67], v[142:145], v[208:211], v[64:67]
	v_mfma_f32_16x16x32_bf16 v[60:63], v[150:153], v[208:211], v[60:63]
	v_mfma_f32_16x16x32_bf16 v[48:51], v[142:145], v[216:219], v[48:51]
	s_mov_b32 m0, s47
	v_mfma_f32_16x16x32_bf16 v[44:47], v[150:153], v[216:219], v[44:47]
	global_load_lds_dwordx4 v2, s[40:41]
	v_mfma_f32_16x16x32_bf16 v[32:35], v[142:145], v[224:227], v[32:35]
	v_mfma_f32_16x16x32_bf16 v[28:31], v[150:153], v[224:227], v[28:31]
	v_mfma_f32_16x16x32_bf16 v[16:19], v[142:145], v[232:235], v[16:19]
	v_mfma_f32_16x16x32_bf16 v[12:15], v[150:153], v[232:235], v[12:15]
	v_mfma_f32_16x16x32_bf16 v[64:67], v[146:149], v[212:215], v[64:67]
	v_mfma_f32_16x16x32_bf16 v[60:63], v[154:157], v[212:215], v[60:63]
	v_mfma_f32_16x16x32_bf16 v[48:51], v[146:149], v[220:223], v[48:51]
	s_mov_b32 m0, s48
	v_mfma_f32_16x16x32_bf16 v[44:47], v[154:157], v[220:223], v[44:47]
	global_load_lds_dwordx4 v132, s[40:41]
	v_mfma_f32_16x16x32_bf16 v[32:35], v[146:149], v[228:231], v[32:35]
	v_mfma_f32_16x16x32_bf16 v[28:31], v[154:157], v[228:231], v[28:31]
	v_mfma_f32_16x16x32_bf16 v[16:19], v[146:149], v[236:239], v[16:19]
	v_mfma_f32_16x16x32_bf16 v[12:15], v[154:157], v[236:239], v[12:15]
	v_mfma_f32_16x16x32_bf16 v[56:59], v[158:161], v[208:211], v[56:59]
	v_mfma_f32_16x16x32_bf16 v[52:55], v[180:183], v[208:211], v[52:55]
	v_mfma_f32_16x16x32_bf16 v[40:43], v[158:161], v[216:219], v[40:43]
	v_mfma_f32_16x16x32_bf16 v[36:39], v[180:183], v[216:219], v[36:39]
	v_mfma_f32_16x16x32_bf16 v[24:27], v[158:161], v[224:227], v[24:27]
	v_mfma_f32_16x16x32_bf16 v[20:23], v[180:183], v[224:227], v[20:23]
	v_mfma_f32_16x16x32_bf16 v[8:11], v[158:161], v[232:235], v[8:11]
	v_mfma_f32_16x16x32_bf16 v[4:7], v[180:183], v[232:235], v[4:7]
	v_mfma_f32_16x16x32_bf16 v[56:59], v[174:177], v[212:215], v[56:59]
	v_mfma_f32_16x16x32_bf16 v[52:55], v[204:207], v[212:215], v[52:55]
	v_mfma_f32_16x16x32_bf16 v[40:43], v[174:177], v[220:223], v[40:43]
	v_mfma_f32_16x16x32_bf16 v[36:39], v[204:207], v[220:223], v[36:39]
	v_mfma_f32_16x16x32_bf16 v[24:27], v[174:177], v[228:231], v[24:27]
	v_mfma_f32_16x16x32_bf16 v[20:23], v[204:207], v[228:231], v[20:23]
	v_mfma_f32_16x16x32_bf16 v[8:11], v[174:177], v[236:239], v[8:11]
	v_mfma_f32_16x16x32_bf16 v[4:7], v[204:207], v[236:239], v[4:7]
	s_setprio 3
	s_barrier
; #define PG8_STAGE(bufoff, gbase, voff) do { _Pragma("unroll") for (int _i = 0; _i < 2; ++_i) \
;         __builtin_amdgcn_global_load_lds((const unsigned*)((const char*)(gbase) + (voff)[_i]), (PG8_LAS unsigned*)(lds + (bufoff) + ldsw + _i * 8192), 16, 0, 0); } while (0)
; #define PG8_LDA(dst, b, h) do { _Pragma("unroll") for (int m = 0; m < 4; ++m) _Pragma("unroll") for (int k = 0; k < 2; ++k) dst[m][k] = *(const PG8_LAS bf16x8*)(lds + PG8_SA(b, h) + aoff + m * 2048 + k * 1024); } while (0)
; #define PG8_LDB(dst, b, h) do { _Pragma("unroll") for (int n = 0; n < 2; ++n) _Pragma("unroll") for (int k = 0; k < 2; ++k) dst[n][k] = *(const PG8_LAS bf16x8*)(lds + PG8_SB(b, h) + boff + n * 2048 + k * 1024); } while (0)
; #define PG8_MMA(ai, bj, At, Bt) do { __builtin_amdgcn_s_setprio(1); _Pragma("unroll") for (int m = 0; m < 4; ++m) _Pragma("unroll") for (int n = 0; n < 2; ++n) _Pragma("unroll") for (int k = 0; k < 2; ++k) \
;         acc[ai][bj][m][n] = __builtin_amdgcn_mfma_f32_16x16x32_bf16(Bt[n][k], At[m][k], acc[ai][bj][m][n], 0, 0, 0); __builtin_amdgcn_s_setprio(0); } while (0)
; #define PG8_WAIT_V(n) asm volatile("s_waitcnt vmcnt(" #n ")" ::: "memory")
; #define PG8_WAIT_L(n) asm volatile("s_waitcnt lgkmcnt(" #n ")" ::: "memory")
; #define PG8_BAR __builtin_amdgcn_s_barrier()
; #define PG8_SCHED __builtin_amdgcn_sched_barrier(0)
; template <class Epi, class Sched, bool ALIGN_EPI = false, bool SP2 = false>
; __device__ __forceinline__ void gemm_phase(PG8_LAS unsigned char* lds, const Gemm g, const Sched& S, const Epi& E) {
;     ...
;             PG8_LDB(B0, 1, 0); PG8_LDB(B1, 1, 1); PG8_SCHED; PG8_LDA(At, 1, 0); PG8_STAGE(PG8_SA(0, 1), a2 + hstep, voffA);
;             PG8_WAIT_V(8); PG8_WAIT_L(0); PG8_BAR; PG8_MMA(0, 0, At, B0); PG8_MMA(0, 1, At, B1); PG8_BAR; PG8_SCHED;
;             PG8_LDA(At, 1, 1); PG8_STAGE(PG8_SB(1, 0), b3, voffB); PG8_STAGE(PG8_SB(1, 1), b3 + hstep, voffB); PG8_STAGE(PG8_SA(1, 0), a3, voffA);
;             PG8_WAIT_V(8); PG8_WAIT_L(0); PG8_BAR; PG8_MMA(1, 0, At, B0); PG8_MMA(1, 1, At, B1); PG8_BAR; PG8_SCHED;
	s_add_i32 s64, 0, 0x18000
	v_add_u32_e32 v135, s64, v173
	s_add_i32 s65, 0, 0x1c000
	ds_read_b128 v[142:145], v135
	ds_read_b128 v[146:149], v135 offset:1024
	ds_read_b128 v[150:153], v135 offset:2048
	ds_read_b128 v[154:157], v135 offset:3072
	v_add_u32_e32 v135, s65, v173
	ds_read_b128 v[158:161], v135
	ds_read_b128 v[174:177], v135 offset:1024
	ds_read_b128 v[180:183], v135 offset:2048
	ds_read_b128 v[204:207], v135 offset:3072
	s_add_u32 s34, s40, 0x158000
	s_addc_u32 s35, s41, 0
	s_mov_b32 m0, s49
	ds_read_b128 v[208:211], v179 offset:32768
	ds_read_b128 v[212:215], v179 offset:33792
	ds_read_b128 v[216:219], v179 offset:34816
	ds_read_b128 v[220:223], v179 offset:35840
	ds_read_b128 v[224:227], v179 offset:36864
	ds_read_b128 v[228:231], v179 offset:37888
	ds_read_b128 v[232:235], v179 offset:38912
	ds_read_b128 v[236:239], v179 offset:39936
	global_load_lds_dwordx4 v2, s[34:35]
	s_waitcnt vmcnt(7)
	s_waitcnt lgkmcnt(0)
	s_barrier
	s_setprio 0
	s_waitcnt lgkmcnt(0)
	v_mfma_f32_16x16x32_bf16 v[128:131], v[142:145], v[208:211], v[128:131]
	v_mfma_f32_16x16x32_bf16 v[124:127], v[150:153], v[208:211], v[124:127]
	v_mfma_f32_16x16x32_bf16 v[112:115], v[142:145], v[216:219], v[112:115]
	s_mov_b32 m0, s50
	v_mfma_f32_16x16x32_bf16 v[108:111], v[150:153], v[216:219], v[108:111]
	global_load_lds_dwordx4 v132, s[34:35]
	v_mfma_f32_16x16x32_bf16 v[96:99], v[142:145], v[224:227], v[96:99]
	v_mfma_f32_16x16x32_bf16 v[92:95], v[150:153], v[224:227], v[92:95]
	v_mfma_f32_16x16x32_bf16 v[80:83], v[142:145], v[232:235], v[80:83]
	v_mfma_f32_16x16x32_bf16 v[76:79], v[150:153], v[232:235], v[76:79]
	v_mfma_f32_16x16x32_bf16 v[128:131], v[146:149], v[212:215], v[128:131]
	v_mfma_f32_16x16x32_bf16 v[124:127], v[154:157], v[212:215], v[124:127]
	v_mfma_f32_16x16x32_bf16 v[112:115], v[146:149], v[220:223], v[112:115]
	v_mfma_f32_16x16x32_bf16 v[108:111], v[154:157], v[220:223], v[108:111]
	v_mfma_f32_16x16x32_bf16 v[96:99], v[146:149], v[228:231], v[96:99]
	v_mfma_f32_16x16x32_bf16 v[92:95], v[154:157], v[228:231], v[92:95]
	v_mfma_f32_16x16x32_bf16 v[80:83], v[146:149], v[236:239], v[80:83]
	v_mfma_f32_16x16x32_bf16 v[76:79], v[154:157], v[236:239], v[76:79]
	v_mfma_f32_16x16x32_bf16 v[120:123], v[158:161], v[208:211], v[120:123]
	v_mfma_f32_16x16x32_bf16 v[116:119], v[180:183], v[208:211], v[116:119]
	v_mfma_f32_16x16x32_bf16 v[104:107], v[158:161], v[216:219], v[104:107]
	v_mfma_f32_16x16x32_bf16 v[100:103], v[180:183], v[216:219], v[100:103]
	v_mfma_f32_16x16x32_bf16 v[88:91], v[158:161], v[224:227], v[88:91]
	v_mfma_f32_16x16x32_bf16 v[84:87], v[180:183], v[224:227], v[84:87]
	v_mfma_f32_16x16x32_bf16 v[72:75], v[158:161], v[232:235], v[72:75]
	v_mfma_f32_16x16x32_bf16 v[68:71], v[180:183], v[232:235], v[68:71]
	v_mfma_f32_16x16x32_bf16 v[120:123], v[174:177], v[212:215], v[120:123]
	v_mfma_f32_16x16x32_bf16 v[116:119], v[204:207], v[212:215], v[116:119]
	v_mfma_f32_16x16x32_bf16 v[104:107], v[174:177], v[220:223], v[104:107]
	v_mfma_f32_16x16x32_bf16 v[100:103], v[204:207], v[220:223], v[100:103]
	v_mfma_f32_16x16x32_bf16 v[88:91], v[174:177], v[228:231], v[88:91]
	v_mfma_f32_16x16x32_bf16 v[84:87], v[204:207], v[228:231], v[84:87]
	v_mfma_f32_16x16x32_bf16 v[72:75], v[174:177], v[236:239], v[72:75]
	v_mfma_f32_16x16x32_bf16 v[68:71], v[204:207], v[236:239], v[68:71]
	s_setprio 3
	s_barrier
	s_add_i32 s34, s64, s46
	s_add_i32 m0, s34, 0xffffff80
	ds_read_b128 v[208:211], v179 offset:49152
	ds_read_b128 v[212:215], v179 offset:50176
	ds_read_b128 v[216:219], v179 offset:51200
	ds_read_b128 v[220:223], v179 offset:52224
	ds_read_b128 v[224:227], v179 offset:53248
	ds_read_b128 v[228:231], v179 offset:54272
	ds_read_b128 v[232:235], v179 offset:55296
	ds_read_b128 v[236:239], v179 offset:56320
	global_load_lds_dwordx4 v2, s[38:39] offset:128
	s_add_i32 m0, s34, 0x1f80
	s_add_u32 s34, s38, 0x158080
	s_addc_u32 s35, s39, 0
	global_load_lds_dwordx4 v132, s[38:39] offset:128
	s_add_i32 s38, s65, s46
	s_mov_b32 m0, s38
	s_nop 0
	global_load_lds_dwordx4 v2, s[34:35]
	s_add_i32 m0, s38, 0x2000
	s_nop 0
	global_load_lds_dwordx4 v132, s[34:35]
	s_waitcnt vmcnt(6)
	s_waitcnt lgkmcnt(0)
	s_barrier
	s_setprio 0
	s_waitcnt lgkmcnt(0)
	v_mfma_f32_16x16x32_bf16 v[64:67], v[142:145], v[208:211], v[64:67]
	v_mfma_f32_16x16x32_bf16 v[60:63], v[150:153], v[208:211], v[60:63]
	v_mfma_f32_16x16x32_bf16 v[48:51], v[142:145], v[216:219], v[48:51]
	s_add_i32 m0, s53, 0xffffff80
	v_mfma_f32_16x16x32_bf16 v[44:47], v[150:153], v[216:219], v[44:47]
	global_load_lds_dwordx4 v2, s[40:41] offset:128
	v_mfma_f32_16x16x32_bf16 v[32:35], v[142:145], v[224:227], v[32:35]
	v_mfma_f32_16x16x32_bf16 v[28:31], v[150:153], v[224:227], v[28:31]
	v_mfma_f32_16x16x32_bf16 v[16:19], v[142:145], v[232:235], v[16:19]
	v_mfma_f32_16x16x32_bf16 v[12:15], v[150:153], v[232:235], v[12:15]
	v_mfma_f32_16x16x32_bf16 v[64:67], v[146:149], v[212:215], v[64:67]
	v_mfma_f32_16x16x32_bf16 v[60:63], v[154:157], v[212:215], v[60:63]
	v_mfma_f32_16x16x32_bf16 v[48:51], v[146:149], v[220:223], v[48:51]
	s_add_i32 m0, s54, 0xffffff80
	v_mfma_f32_16x16x32_bf16 v[44:47], v[154:157], v[220:223], v[44:47]
	global_load_lds_dwordx4 v132, s[40:41] offset:128
	v_mfma_f32_16x16x32_bf16 v[32:35], v[146:149], v[228:231], v[32:35]
	v_mfma_f32_16x16x32_bf16 v[28:31], v[154:157], v[228:231], v[28:31]
	v_mfma_f32_16x16x32_bf16 v[16:19], v[146:149], v[236:239], v[16:19]
	v_mfma_f32_16x16x32_bf16 v[12:15], v[154:157], v[236:239], v[12:15]
	v_mfma_f32_16x16x32_bf16 v[56:59], v[158:161], v[208:211], v[56:59]
	v_mfma_f32_16x16x32_bf16 v[52:55], v[180:183], v[208:211], v[52:55]
	v_mfma_f32_16x16x32_bf16 v[40:43], v[158:161], v[216:219], v[40:43]
	v_mfma_f32_16x16x32_bf16 v[36:39], v[180:183], v[216:219], v[36:39]
	v_mfma_f32_16x16x32_bf16 v[24:27], v[158:161], v[224:227], v[24:27]
	v_mfma_f32_16x16x32_bf16 v[20:23], v[180:183], v[224:227], v[20:23]
	v_mfma_f32_16x16x32_bf16 v[8:11], v[158:161], v[232:235], v[8:11]
	v_mfma_f32_16x16x32_bf16 v[4:7], v[180:183], v[232:235], v[4:7]
	v_mfma_f32_16x16x32_bf16 v[56:59], v[174:177], v[212:215], v[56:59]
	v_mfma_f32_16x16x32_bf16 v[52:55], v[204:207], v[212:215], v[52:55]
	v_mfma_f32_16x16x32_bf16 v[40:43], v[174:177], v[220:223], v[40:43]
	v_mfma_f32_16x16x32_bf16 v[36:39], v[204:207], v[220:223], v[36:39]
	v_mfma_f32_16x16x32_bf16 v[24:27], v[174:177], v[228:231], v[24:27]
	v_mfma_f32_16x16x32_bf16 v[20:23], v[204:207], v[228:231], v[20:23]
	v_mfma_f32_16x16x32_bf16 v[8:11], v[174:177], v[236:239], v[8:11]
	v_mfma_f32_16x16x32_bf16 v[4:7], v[204:207], v[236:239], v[4:7]
	s_setprio 3
	s_barrier
	s_add_i32 s63, s63, 2
	s_add_u32 s61, s61, 0x100
	s_addc_u32 s62, s62, 0
	s_cmpk_gt_u32 s63, 0x53
	s_mov_b64 s[34:35], s[36:37]
	s_cbranch_scc0 .LBB0_575
	s_and_b64 vcc, exec, s[28:29]
	s_cbranch_vccz .LBB0_578
	s_barrier

; #define PG8_STAGE(bufoff, gbase, voff) do { _Pragma("unroll") for (int _i = 0; _i < 2; ++_i) \
;         __builtin_amdgcn_global_load_lds((const unsigned*)((const char*)(gbase) + (voff)[_i]), (PG8_LAS unsigned*)(lds + (bufoff) + ldsw + _i * 8192), 16, 0, 0); } while (0)
; #define PG8_LDA(dst, b, h) do { _Pragma("unroll") for (int m = 0; m < 4; ++m) _Pragma("unroll") for (int k = 0; k < 2; ++k) dst[m][k] = *(const PG8_LAS bf16x8*)(lds + PG8_SA(b, h) + aoff + m * 2048 + k * 1024); } while (0)
; #define PG8_LDB(dst, b, h) do { _Pragma("unroll") for (int n = 0; n < 2; ++n) _Pragma("unroll") for (int k = 0; k < 2; ++k) dst[n][k] = *(const PG8_LAS bf16x8*)(lds + PG8_SB(b, h) + boff + n * 2048 + k * 1024); } while (0)
; #define PG8_MMA(ai, bj, At, Bt) do { __builtin_amdgcn_s_setprio(1); _Pragma("unroll") for (int m = 0; m < 4; ++m) _Pragma("unroll") for (int n = 0; n < 2; ++n) _Pragma("unroll") for (int k = 0; k < 2; ++k) \
;         acc[ai][bj][m][n] = __builtin_amdgcn_mfma_f32_16x16x32_bf16(Bt[n][k], At[m][k], acc[ai][bj][m][n], 0, 0, 0); __builtin_amdgcn_s_setprio(0); } while (0)
; #define PG8_WAIT_V(n) asm volatile("s_waitcnt vmcnt(" #n ")" ::: "memory")
; #define PG8_WAIT_L(n) asm volatile("s_waitcnt lgkmcnt(" #n ")" ::: "memory")
; template <class Epi, class Sched, bool ALIGN_EPI = false, bool SP2 = false>
; __device__ __forceinline__ void gemm_phase(PG8_LAS unsigned char* lds, const Gemm g, const Sched& S, const Epi& E) {
;     ...
;             const bool last = (t == nt - 2);
;             const char* a1 = cA + (size_t)(t + 1) * kstep;
;             const char* a2 = last ? nA : cA + (size_t)(t + 2) * kstep; const char* b2 = last ? nB : cB + (size_t)(t + 2) * kstep;
;             const char* a3 = a2 + kstep; const char* b3 = b2 + kstep;
;             if (last && has_next) S.a_ready(nxt);
;             if constexpr (SP2) {
;             PG8_LDB(B0, 0, 0); PG8_LDB(B1, 0, 1); PG8_SCHED; PG8_LDA(At, 0, 0); PG8_STAGE(PG8_SA(1, 1), a1 + hstep, voffA);
;             PG8_WAIT_V(8); PG8_WAIT_L(0); PG8_BAR; PG8_MMA(0, 0, At, B0); PG8_MMA(0, 1, At, B1); PG8_BAR; PG8_SCHED;
;             PG8_LDA(At, 0, 1); PG8_STAGE(PG8_SB(0, 0), b2, voffB); PG8_STAGE(PG8_SB(0, 1), b2 + hstep, voffB); PG8_STAGE(PG8_SA(0, 0), a2, voffA);
;             PG8_WAIT_V(8); PG8_WAIT_L(0); PG8_BAR; PG8_MMA(1, 0, At, B0); PG8_MMA(1, 1, At, B1); PG8_BAR; PG8_SCHED;
.LBB0_674:
	s_add_u32 s42, s40, 0xfff80080
	s_addc_u32 s43, s41, -1
	s_add_i32 s64, 0, 0x10000
	s_cmp_eq_u32 s63, 28
	s_cselect_b32 s45, s5, s43
	s_cselect_b32 s44, s4, s42
	s_cselect_b32 s43, s37, s62
	s_cselect_b32 s42, s36, s35
	s_add_i32 s66, 0, 0x14000
	v_add_u32_e32 v144, s64, v173
	v_add_u32_e32 v162, s66, v173
	ds_read_b128 v[132:135], v144
	ds_read_b128 v[136:139], v144 offset:1024
	ds_read_b128 v[140:143], v144 offset:2048
	ds_read_b128 v[144:147], v144 offset:3072
	ds_read_b128 v[158:161], v162
	ds_read_b128 v[174:177], v162 offset:1024
	ds_read_b128 v[206:209], v162 offset:2048
	ds_read_b128 v[210:213], v162 offset:3072
	s_add_i32 m0, s39, 0xc000
	ds_read_b128 v[214:217], v204
	ds_read_b128 v[218:221], v204 offset:1024
	ds_read_b128 v[222:225], v204 offset:2048
	ds_read_b128 v[226:229], v204 offset:3072
	ds_read_b128 v[230:233], v204 offset:4096
	ds_read_b128 v[234:237], v204 offset:5120
	ds_read_b128 v[238:241], v204 offset:6144
	ds_read_b128 v[242:245], v204 offset:7168
	global_load_lds_dwordx4 v154, s[40:41]
	s_nop 0
	s_waitcnt vmcnt(7)
	s_waitcnt lgkmcnt(0)
	s_barrier
	s_setprio 0
	s_waitcnt lgkmcnt(0)
	v_mfma_f32_16x16x32_bf16 v[128:131], v[132:135], v[214:217], v[128:131]
	v_mfma_f32_16x16x32_bf16 v[124:127], v[140:143], v[214:217], v[124:127]
	v_mfma_f32_16x16x32_bf16 v[116:119], v[132:135], v[222:225], v[116:119]
	s_add_i32 m0, s39, 0xe000
	v_mfma_f32_16x16x32_bf16 v[108:111], v[140:143], v[222:225], v[108:111]
	global_load_lds_dwordx4 v156, s[40:41]
	v_mfma_f32_16x16x32_bf16 v[100:103], v[132:135], v[230:233], v[100:103]
	v_mfma_f32_16x16x32_bf16 v[92:95], v[140:143], v[230:233], v[92:95]
	v_mfma_f32_16x16x32_bf16 v[84:87], v[132:135], v[238:241], v[84:87]
	v_mfma_f32_16x16x32_bf16 v[76:79], v[140:143], v[238:241], v[76:79]
	v_mfma_f32_16x16x32_bf16 v[128:131], v[136:139], v[218:221], v[128:131]
	v_mfma_f32_16x16x32_bf16 v[124:127], v[144:147], v[218:221], v[124:127]
	v_mfma_f32_16x16x32_bf16 v[116:119], v[136:139], v[226:229], v[116:119]
	v_mfma_f32_16x16x32_bf16 v[108:111], v[144:147], v[226:229], v[108:111]
	v_mfma_f32_16x16x32_bf16 v[100:103], v[136:139], v[234:237], v[100:103]
	v_mfma_f32_16x16x32_bf16 v[92:95], v[144:147], v[234:237], v[92:95]
	v_mfma_f32_16x16x32_bf16 v[84:87], v[136:139], v[242:245], v[84:87]
	v_mfma_f32_16x16x32_bf16 v[76:79], v[144:147], v[242:245], v[76:79]
	v_mfma_f32_16x16x32_bf16 v[120:123], v[158:161], v[214:217], v[120:123]
	v_mfma_f32_16x16x32_bf16 v[112:115], v[206:209], v[214:217], v[112:115]
	v_mfma_f32_16x16x32_bf16 v[104:107], v[158:161], v[222:225], v[104:107]
	v_mfma_f32_16x16x32_bf16 v[96:99], v[206:209], v[222:225], v[96:99]
	v_mfma_f32_16x16x32_bf16 v[88:91], v[158:161], v[230:233], v[88:91]
	v_mfma_f32_16x16x32_bf16 v[80:83], v[206:209], v[230:233], v[80:83]
	v_mfma_f32_16x16x32_bf16 v[72:75], v[158:161], v[238:241], v[72:75]
	v_mfma_f32_16x16x32_bf16 v[68:71], v[206:209], v[238:241], v[68:71]
	v_mfma_f32_16x16x32_bf16 v[120:123], v[174:177], v[218:221], v[120:123]
	v_mfma_f32_16x16x32_bf16 v[112:115], v[210:213], v[218:221], v[112:115]
	v_mfma_f32_16x16x32_bf16 v[104:107], v[174:177], v[226:229], v[104:107]
	v_mfma_f32_16x16x32_bf16 v[96:99], v[210:213], v[226:229], v[96:99]
	v_mfma_f32_16x16x32_bf16 v[88:91], v[174:177], v[234:237], v[88:91]
	v_mfma_f32_16x16x32_bf16 v[80:83], v[210:213], v[234:237], v[80:83]
	v_mfma_f32_16x16x32_bf16 v[72:75], v[174:177], v[242:245], v[72:75]
	v_mfma_f32_16x16x32_bf16 v[68:71], v[210:213], v[242:245], v[68:71]
	s_setprio 3
	s_barrier
	s_add_i32 s64, s64, s46
	s_mov_b32 m0, s64
	ds_read_b128 v[214:217], v204 offset:16384
	ds_read_b128 v[218:221], v204 offset:17408
	ds_read_b128 v[222:225], v204 offset:18432
	ds_read_b128 v[226:229], v204 offset:19456
	ds_read_b128 v[230:233], v204 offset:20480
	ds_read_b128 v[234:237], v204 offset:21504
	ds_read_b128 v[238:241], v204 offset:22528
	ds_read_b128 v[242:245], v204 offset:23552
	global_load_lds_dwordx4 v2, s[42:43]
	s_add_i32 m0, s64, 0x2000
	s_add_u32 s64, s42, 0x80000
	s_addc_u32 s65, s43, 0
	s_add_i32 s66, s66, s46
	global_load_lds_dwordx4 v148, s[42:43]
	s_mov_b32 m0, s66
	s_nop 0
	global_load_lds_dwordx4 v2, s[64:65]
	s_add_i32 m0, s66, 0x2000
	s_nop 0
	global_load_lds_dwordx4 v148, s[64:65]
	s_nop 0
	s_nop 0
	s_nop 0
	s_nop 0
	s_nop 0
	s_nop 0
	s_nop 0
	s_waitcnt vmcnt(6)
	s_waitcnt lgkmcnt(0)
	s_barrier
	s_setprio 0
	s_waitcnt lgkmcnt(0)
	v_mfma_f32_16x16x32_bf16 v[64:67], v[132:135], v[214:217], v[64:67]
	v_mfma_f32_16x16x32_bf16 v[60:63], v[140:143], v[214:217], v[60:63]
	v_mfma_f32_16x16x32_bf16 v[52:55], v[132:135], v[222:225], v[52:55]
	s_mov_b32 m0, s39
	v_mfma_f32_16x16x32_bf16 v[44:47], v[140:143], v[222:225], v[44:47]
	global_load_lds_dwordx4 v152, s[44:45]
	v_mfma_f32_16x16x32_bf16 v[36:39], v[132:135], v[230:233], v[36:39]
	v_mfma_f32_16x16x32_bf16 v[28:31], v[140:143], v[230:233], v[28:31]
	v_mfma_f32_16x16x32_bf16 v[20:23], v[132:135], v[238:241], v[20:23]
	v_mfma_f32_16x16x32_bf16 v[12:15], v[140:143], v[238:241], v[12:15]
	v_mfma_f32_16x16x32_bf16 v[64:67], v[136:139], v[218:221], v[64:67]
	v_mfma_f32_16x16x32_bf16 v[60:63], v[144:147], v[218:221], v[60:63]
	v_mfma_f32_16x16x32_bf16 v[52:55], v[136:139], v[226:229], v[52:55]
	s_mov_b32 m0, s51
	v_mfma_f32_16x16x32_bf16 v[44:47], v[144:147], v[226:229], v[44:47]
	global_load_lds_dwordx4 v150, s[44:45]
	v_mfma_f32_16x16x32_bf16 v[36:39], v[136:139], v[234:237], v[36:39]
	v_mfma_f32_16x16x32_bf16 v[28:31], v[144:147], v[234:237], v[28:31]
	v_mfma_f32_16x16x32_bf16 v[20:23], v[136:139], v[242:245], v[20:23]
	v_mfma_f32_16x16x32_bf16 v[12:15], v[144:147], v[242:245], v[12:15]
	v_mfma_f32_16x16x32_bf16 v[56:59], v[158:161], v[214:217], v[56:59]
	v_mfma_f32_16x16x32_bf16 v[48:51], v[206:209], v[214:217], v[48:51]
	v_mfma_f32_16x16x32_bf16 v[40:43], v[158:161], v[222:225], v[40:43]
	v_mfma_f32_16x16x32_bf16 v[32:35], v[206:209], v[222:225], v[32:35]
	v_mfma_f32_16x16x32_bf16 v[24:27], v[158:161], v[230:233], v[24:27]
	v_mfma_f32_16x16x32_bf16 v[16:19], v[206:209], v[230:233], v[16:19]
	v_mfma_f32_16x16x32_bf16 v[8:11], v[158:161], v[238:241], v[8:11]
	v_mfma_f32_16x16x32_bf16 v[4:7], v[206:209], v[238:241], v[4:7]
	v_mfma_f32_16x16x32_bf16 v[56:59], v[174:177], v[218:221], v[56:59]
	v_mfma_f32_16x16x32_bf16 v[48:51], v[210:213], v[218:221], v[48:51]
	v_mfma_f32_16x16x32_bf16 v[40:43], v[174:177], v[226:229], v[40:43]
	v_mfma_f32_16x16x32_bf16 v[32:35], v[210:213], v[226:229], v[32:35]
	v_mfma_f32_16x16x32_bf16 v[24:27], v[174:177], v[234:237], v[24:27]
	v_mfma_f32_16x16x32_bf16 v[16:19], v[210:213], v[234:237], v[16:19]
	v_mfma_f32_16x16x32_bf16 v[8:11], v[174:177], v[242:245], v[8:11]
	v_mfma_f32_16x16x32_bf16 v[4:7], v[210:213], v[242:245], v[4:7]
	s_setprio 3
	s_barrier
; #define PG8_STAGE(bufoff, gbase, voff) do { _Pragma("unroll") for (int _i = 0; _i < 2; ++_i) \
;         __builtin_amdgcn_global_load_lds((const unsigned*)((const char*)(gbase) + (voff)[_i]), (PG8_LAS unsigned*)(lds + (bufoff) + ldsw + _i * 8192), 16, 0, 0); } while (0)
; #define PG8_LDA(dst, b, h) do { _Pragma("unroll") for (int m = 0; m < 4; ++m) _Pragma("unroll") for (int k = 0; k < 2; ++k) dst[m][k] = *(const PG8_LAS bf16x8*)(lds + PG8_SA(b, h) + aoff + m * 2048 + k * 1024); } while (0)
; #define PG8_LDB(dst, b, h) do { _Pragma("unroll") for (int n = 0; n < 2; ++n) _Pragma("unroll") for (int k = 0; k < 2; ++k) dst[n][k] = *(const PG8_LAS bf16x8*)(lds + PG8_SB(b, h) + boff + n * 2048 + k * 1024); } while (0)
; #define PG8_MMA(ai, bj, At, Bt) do { __builtin_amdgcn_s_setprio(1); _Pragma("unroll") for (int m = 0; m < 4; ++m) _Pragma("unroll") for (int n = 0; n < 2; ++n) _Pragma("unroll") for (int k = 0; k < 2; ++k) \
;         acc[ai][bj][m][n] = __builtin_amdgcn_mfma_f32_16x16x32_bf16(Bt[n][k], At[m][k], acc[ai][bj][m][n], 0, 0, 0); __builtin_amdgcn_s_setprio(0); } while (0)
; #define PG8_WAIT_V(n) asm volatile("s_waitcnt vmcnt(" #n ")" ::: "memory")
; #define PG8_WAIT_L(n) asm volatile("s_waitcnt lgkmcnt(" #n ")" ::: "memory")
; #define PG8_BAR __builtin_amdgcn_s_barrier()
; #define PG8_SCHED __builtin_amdgcn_sched_barrier(0)
; template <class Epi, class Sched, bool ALIGN_EPI = false, bool SP2 = false>
; __device__ __forceinline__ void gemm_phase(PG8_LAS unsigned char* lds, const Gemm g, const Sched& S, const Epi& E) {
;     ...
;             PG8_LDB(B0, 1, 0); PG8_LDB(B1, 1, 1); PG8_SCHED; PG8_LDA(At, 1, 0); PG8_STAGE(PG8_SA(0, 1), a2 + hstep, voffA);
;             PG8_WAIT_V(8); PG8_WAIT_L(0); PG8_BAR; PG8_MMA(0, 0, At, B0); PG8_MMA(0, 1, At, B1); PG8_BAR; PG8_SCHED;
;             PG8_LDA(At, 1, 1); PG8_STAGE(PG8_SB(1, 0), b3, voffB); PG8_STAGE(PG8_SB(1, 1), b3 + hstep, voffB); PG8_STAGE(PG8_SA(1, 0), a3, voffA);
;             PG8_WAIT_V(8); PG8_WAIT_L(0); PG8_BAR; PG8_MMA(1, 0, At, B0); PG8_MMA(1, 1, At, B1); PG8_BAR; PG8_SCHED;
	s_add_i32 s64, 0, 0x18000
	s_add_i32 s65, 0, 0x1c000
	v_add_u32_e32 v144, s64, v173
	v_add_u32_e32 v164, s65, v173
	ds_read_b128 v[132:135], v144
	ds_read_b128 v[136:139], v144 offset:1024
	ds_read_b128 v[140:143], v144 offset:2048
	ds_read_b128 v[144:147], v144 offset:3072
	ds_read_b128 v[158:161], v164
	ds_read_b128 v[174:177], v164 offset:1024
	ds_read_b128 v[206:209], v164 offset:2048
	ds_read_b128 v[210:213], v164 offset:3072
	s_add_u32 s100, s44, 0x80
	s_addc_u32 s101, s45, 0
	s_add_u32 s44, s44, 0x80000
	s_addc_u32 s45, s45, 0
	s_mov_b32 m0, s52
	ds_read_b128 v[214:217], v204 offset:32768
	ds_read_b128 v[218:221], v204 offset:33792
	ds_read_b128 v[222:225], v204 offset:34816
	ds_read_b128 v[226:229], v204 offset:35840
	ds_read_b128 v[230:233], v204 offset:36864
	ds_read_b128 v[234:237], v204 offset:37888
	ds_read_b128 v[238:241], v204 offset:38912
	ds_read_b128 v[242:245], v204 offset:39936
	global_load_lds_dwordx4 v152, s[44:45]
	s_waitcnt vmcnt(7)
	s_waitcnt lgkmcnt(0)
	s_barrier
	s_setprio 0
	s_waitcnt lgkmcnt(0)
	v_mfma_f32_16x16x32_bf16 v[128:131], v[132:135], v[214:217], v[128:131]
	v_mfma_f32_16x16x32_bf16 v[124:127], v[140:143], v[214:217], v[124:127]
	v_mfma_f32_16x16x32_bf16 v[116:119], v[132:135], v[222:225], v[116:119]
	s_mov_b32 m0, s53
	v_mfma_f32_16x16x32_bf16 v[108:111], v[140:143], v[222:225], v[108:111]
	global_load_lds_dwordx4 v150, s[44:45]
	v_mfma_f32_16x16x32_bf16 v[100:103], v[132:135], v[230:233], v[100:103]
	v_mfma_f32_16x16x32_bf16 v[92:95], v[140:143], v[230:233], v[92:95]
	v_mfma_f32_16x16x32_bf16 v[84:87], v[132:135], v[238:241], v[84:87]
	v_mfma_f32_16x16x32_bf16 v[76:79], v[140:143], v[238:241], v[76:79]
	v_mfma_f32_16x16x32_bf16 v[128:131], v[136:139], v[218:221], v[128:131]
	v_mfma_f32_16x16x32_bf16 v[124:127], v[144:147], v[218:221], v[124:127]
	v_mfma_f32_16x16x32_bf16 v[116:119], v[136:139], v[226:229], v[116:119]
	v_mfma_f32_16x16x32_bf16 v[108:111], v[144:147], v[226:229], v[108:111]
	v_mfma_f32_16x16x32_bf16 v[100:103], v[136:139], v[234:237], v[100:103]
	v_mfma_f32_16x16x32_bf16 v[92:95], v[144:147], v[234:237], v[92:95]
	v_mfma_f32_16x16x32_bf16 v[84:87], v[136:139], v[242:245], v[84:87]
	v_mfma_f32_16x16x32_bf16 v[76:79], v[144:147], v[242:245], v[76:79]
	v_mfma_f32_16x16x32_bf16 v[120:123], v[158:161], v[214:217], v[120:123]
	v_mfma_f32_16x16x32_bf16 v[112:115], v[206:209], v[214:217], v[112:115]
	v_mfma_f32_16x16x32_bf16 v[104:107], v[158:161], v[222:225], v[104:107]
	v_mfma_f32_16x16x32_bf16 v[96:99], v[206:209], v[222:225], v[96:99]
	v_mfma_f32_16x16x32_bf16 v[88:91], v[158:161], v[230:233], v[88:91]
	v_mfma_f32_16x16x32_bf16 v[80:83], v[206:209], v[230:233], v[80:83]
	v_mfma_f32_16x16x32_bf16 v[72:75], v[158:161], v[238:241], v[72:75]
	v_mfma_f32_16x16x32_bf16 v[68:71], v[206:209], v[238:241], v[68:71]
	v_mfma_f32_16x16x32_bf16 v[120:123], v[174:177], v[218:221], v[120:123]
	v_mfma_f32_16x16x32_bf16 v[112:115], v[210:213], v[218:221], v[112:115]
	v_mfma_f32_16x16x32_bf16 v[104:107], v[174:177], v[226:229], v[104:107]
	v_mfma_f32_16x16x32_bf16 v[96:99], v[210:213], v[226:229], v[96:99]
	v_mfma_f32_16x16x32_bf16 v[88:91], v[174:177], v[234:237], v[88:91]
	v_mfma_f32_16x16x32_bf16 v[80:83], v[210:213], v[234:237], v[80:83]
	v_mfma_f32_16x16x32_bf16 v[72:75], v[174:177], v[242:245], v[72:75]
	v_mfma_f32_16x16x32_bf16 v[68:71], v[210:213], v[242:245], v[68:71]
	s_setprio 3
	s_barrier
	s_add_i32 s44, s64, s46
	s_add_i32 m0, s44, 0xffffff80
	ds_read_b128 v[214:217], v204 offset:49152
	ds_read_b128 v[218:221], v204 offset:50176
	ds_read_b128 v[222:225], v204 offset:51200
	ds_read_b128 v[226:229], v204 offset:52224
	ds_read_b128 v[230:233], v204 offset:53248
	ds_read_b128 v[234:237], v204 offset:54272
	ds_read_b128 v[238:241], v204 offset:55296
	ds_read_b128 v[242:245], v204 offset:56320
	global_load_lds_dwordx4 v2, s[42:43] offset:128
	s_add_i32 m0, s44, 0x1f80
	s_add_i32 s44, s65, s46
	global_load_lds_dwordx4 v148, s[42:43] offset:128
	s_add_u32 s42, s42, 0x80080
	s_addc_u32 s43, s43, 0
	s_mov_b32 m0, s44
	s_nop 0
	global_load_lds_dwordx4 v2, s[42:43]
	s_add_i32 m0, s44, 0x2000
	s_nop 0
	global_load_lds_dwordx4 v148, s[42:43]
	s_waitcnt vmcnt(6)
	s_waitcnt lgkmcnt(0)
	s_barrier
	s_setprio 0
	s_waitcnt lgkmcnt(0)
	v_mfma_f32_16x16x32_bf16 v[64:67], v[132:135], v[214:217], v[64:67]
	v_mfma_f32_16x16x32_bf16 v[60:63], v[140:143], v[214:217], v[60:63]
	v_mfma_f32_16x16x32_bf16 v[52:55], v[132:135], v[222:225], v[52:55]
	s_mov_b32 m0, s54
	v_mfma_f32_16x16x32_bf16 v[44:47], v[140:143], v[222:225], v[44:47]
	global_load_lds_dwordx4 v152, s[100:101]
	v_mfma_f32_16x16x32_bf16 v[36:39], v[132:135], v[230:233], v[36:39]
	v_mfma_f32_16x16x32_bf16 v[28:31], v[140:143], v[230:233], v[28:31]
	v_mfma_f32_16x16x32_bf16 v[20:23], v[132:135], v[238:241], v[20:23]
	v_mfma_f32_16x16x32_bf16 v[12:15], v[140:143], v[238:241], v[12:15]
	v_mfma_f32_16x16x32_bf16 v[64:67], v[136:139], v[218:221], v[64:67]
	v_mfma_f32_16x16x32_bf16 v[60:63], v[144:147], v[218:221], v[60:63]
	v_mfma_f32_16x16x32_bf16 v[52:55], v[136:139], v[226:229], v[52:55]
	s_mov_b32 m0, s55
	v_mfma_f32_16x16x32_bf16 v[44:47], v[144:147], v[226:229], v[44:47]
	global_load_lds_dwordx4 v150, s[100:101]
	v_mfma_f32_16x16x32_bf16 v[36:39], v[136:139], v[234:237], v[36:39]
	v_mfma_f32_16x16x32_bf16 v[28:31], v[144:147], v[234:237], v[28:31]
	v_mfma_f32_16x16x32_bf16 v[20:23], v[136:139], v[242:245], v[20:23]
	v_mfma_f32_16x16x32_bf16 v[12:15], v[144:147], v[242:245], v[12:15]
	v_mfma_f32_16x16x32_bf16 v[56:59], v[158:161], v[214:217], v[56:59]
	v_mfma_f32_16x16x32_bf16 v[48:51], v[206:209], v[214:217], v[48:51]
	v_mfma_f32_16x16x32_bf16 v[40:43], v[158:161], v[222:225], v[40:43]
	v_mfma_f32_16x16x32_bf16 v[32:35], v[206:209], v[222:225], v[32:35]
	v_mfma_f32_16x16x32_bf16 v[24:27], v[158:161], v[230:233], v[24:27]
	v_mfma_f32_16x16x32_bf16 v[16:19], v[206:209], v[230:233], v[16:19]
	v_mfma_f32_16x16x32_bf16 v[8:11], v[158:161], v[238:241], v[8:11]
	v_mfma_f32_16x16x32_bf16 v[4:7], v[206:209], v[238:241], v[4:7]
	v_mfma_f32_16x16x32_bf16 v[56:59], v[174:177], v[218:221], v[56:59]
	v_mfma_f32_16x16x32_bf16 v[48:51], v[210:213], v[218:221], v[48:51]
	v_mfma_f32_16x16x32_bf16 v[40:43], v[174:177], v[226:229], v[40:43]
	v_mfma_f32_16x16x32_bf16 v[32:35], v[210:213], v[226:229], v[32:35]
	v_mfma_f32_16x16x32_bf16 v[24:27], v[174:177], v[234:237], v[24:27]
	v_mfma_f32_16x16x32_bf16 v[16:19], v[210:213], v[234:237], v[16:19]
	v_mfma_f32_16x16x32_bf16 v[8:11], v[174:177], v[242:245], v[8:11]
	v_mfma_f32_16x16x32_bf16 v[4:7], v[210:213], v[242:245], v[4:7]
	s_setprio 3
	s_barrier
	s_add_i32 s63, s63, 2
	s_add_u32 s40, s40, 0x100
	s_addc_u32 s41, s41, 0
	s_add_u32 s35, s35, 0x100
	s_addc_u32 s62, s62, 0
	s_cmp_gt_u32 s63, 29
	s_cbranch_scc0 .LBB0_674
	s_and_b64 vcc, exec, s[30:31]
	s_cbranch_vccz .LBB0_677
	s_barrier

; #define PG8_STAGE(bufoff, gbase, voff) do { _Pragma("unroll") for (int _i = 0; _i < 2; ++_i) \
;         __builtin_amdgcn_global_load_lds((const unsigned*)((const char*)(gbase) + (voff)[_i]), (PG8_LAS unsigned*)(lds + (bufoff) + ldsw + _i * 8192), 16, 0, 0); } while (0)
; #define PG8_LDA(dst, b, h) do { _Pragma("unroll") for (int m = 0; m < 4; ++m) _Pragma("unroll") for (int k = 0; k < 2; ++k) dst[m][k] = *(const PG8_LAS bf16x8*)(lds + PG8_SA(b, h) + aoff + m * 2048 + k * 1024); } while (0)
; #define PG8_LDB(dst, b, h) do { _Pragma("unroll") for (int n = 0; n < 2; ++n) _Pragma("unroll") for (int k = 0; k < 2; ++k) dst[n][k] = *(const PG8_LAS bf16x8*)(lds + PG8_SB(b, h) + boff + n * 2048 + k * 1024); } while (0)
; #define PG8_MMA(ai, bj, At, Bt) do { __builtin_amdgcn_s_setprio(1); _Pragma("unroll") for (int m = 0; m < 4; ++m) _Pragma("unroll") for (int n = 0; n < 2; ++n) _Pragma("unroll") for (int k = 0; k < 2; ++k) \
;         acc[ai][bj][m][n] = __builtin_amdgcn_mfma_f32_16x16x32_bf16(Bt[n][k], At[m][k], acc[ai][bj][m][n], 0, 0, 0); __builtin_amdgcn_s_setprio(0); } while (0)
; #define PG8_WAIT_V(n) asm volatile("s_waitcnt vmcnt(" #n ")" ::: "memory")
; #define PG8_WAIT_L(n) asm volatile("s_waitcnt lgkmcnt(" #n ")" ::: "memory")
; template <class Epi, class Sched, bool ALIGN_EPI = false, bool SP2 = false>
; __device__ __forceinline__ void gemm_phase(PG8_LAS unsigned char* lds, const Gemm g, const Sched& S, const Epi& E) {
;     ...
;             const bool last = (t == nt - 2);
;             const char* a1 = cA + (size_t)(t + 1) * kstep;
;             const char* a2 = last ? nA : cA + (size_t)(t + 2) * kstep; const char* b2 = last ? nB : cB + (size_t)(t + 2) * kstep;
;             const char* a3 = a2 + kstep; const char* b3 = b2 + kstep;
;             if (last && has_next) S.a_ready(nxt);
;             if constexpr (SP2) {
;             PG8_LDB(B0, 0, 0); PG8_LDB(B1, 0, 1); PG8_SCHED; PG8_LDA(At, 0, 0); PG8_STAGE(PG8_SA(1, 1), a1 + hstep, voffA);
;             PG8_WAIT_V(8); PG8_WAIT_L(0); PG8_BAR; PG8_MMA(0, 0, At, B0); PG8_MMA(0, 1, At, B1); PG8_BAR; PG8_SCHED;
;             PG8_LDA(At, 0, 1); PG8_STAGE(PG8_SB(0, 0), b2, voffB); PG8_STAGE(PG8_SB(0, 1), b2 + hstep, voffB); PG8_STAGE(PG8_SA(0, 0), a2, voffA);
;             PG8_WAIT_V(8); PG8_WAIT_L(0); PG8_BAR; PG8_MMA(1, 0, At, B0); PG8_MMA(1, 1, At, B1); PG8_BAR; PG8_SCHED;
.LBB0_2096:
	s_add_u32 s27, s40, 0xfffc0080
	s_addc_u32 s29, s41, -1
	s_add_i32 s31, 0, 0x10000
	s_cmp_eq_u32 s26, 12
	s_cselect_b32 s45, s1, s29
	s_cselect_b32 s44, s0, s27
	v_add_u32_e32 v2, s31, v173
	s_cselect_b32 s43, s35, s13
	s_cselect_b32 s42, s34, s11
	s_add_i32 s27, 0, 0x14000
	ds_read_b128 v[134:137], v2
	ds_read_b128 v[138:141], v2 offset:1024
	ds_read_b128 v[154:157], v2 offset:2048
	ds_read_b128 v[158:161], v2 offset:3072
	v_add_u32_e32 v2, s27, v173
	ds_read_b128 v[178:181], v2
	ds_read_b128 v[204:207], v2 offset:1024
	ds_read_b128 v[208:211], v2 offset:2048
	ds_read_b128 v[212:215], v2 offset:3072
	s_add_i32 m0, s55, 0xc000
	ds_read_b128 v[216:219], v177
	ds_read_b128 v[220:223], v177 offset:1024
	ds_read_b128 v[224:227], v177 offset:2048
	ds_read_b128 v[228:231], v177 offset:3072
	ds_read_b128 v[232:235], v177 offset:4096
	ds_read_b128 v[236:239], v177 offset:5120
	ds_read_b128 v[240:243], v177 offset:6144
	ds_read_b128 v[244:247], v177 offset:7168
	global_load_lds_dwordx4 v150, s[40:41]
	s_nop 0
	s_waitcnt vmcnt(7)
	s_waitcnt lgkmcnt(0)
	s_barrier
	s_setprio 0
	s_waitcnt lgkmcnt(0)
	v_mfma_f32_16x16x32_bf16 v[130:133], v[134:137], v[216:219], v[130:133]
	v_mfma_f32_16x16x32_bf16 v[126:129], v[154:157], v[216:219], v[126:129]
	v_mfma_f32_16x16x32_bf16 v[122:125], v[134:137], v[224:227], v[122:125]
	s_add_i32 m0, s55, 0xe000
	v_mfma_f32_16x16x32_bf16 v[118:121], v[154:157], v[224:227], v[118:121]
	global_load_lds_dwordx4 v152, s[40:41]
	v_mfma_f32_16x16x32_bf16 v[114:117], v[134:137], v[232:235], v[114:117]
	v_mfma_f32_16x16x32_bf16 v[110:113], v[154:157], v[232:235], v[110:113]
	v_mfma_f32_16x16x32_bf16 v[106:109], v[134:137], v[240:243], v[106:109]
	v_mfma_f32_16x16x32_bf16 v[102:105], v[154:157], v[240:243], v[102:105]
	v_mfma_f32_16x16x32_bf16 v[130:133], v[138:141], v[220:223], v[130:133]
	v_mfma_f32_16x16x32_bf16 v[126:129], v[158:161], v[220:223], v[126:129]
	v_mfma_f32_16x16x32_bf16 v[122:125], v[138:141], v[228:231], v[122:125]
	v_mfma_f32_16x16x32_bf16 v[118:121], v[158:161], v[228:231], v[118:121]
	v_mfma_f32_16x16x32_bf16 v[114:117], v[138:141], v[236:239], v[114:117]
	v_mfma_f32_16x16x32_bf16 v[110:113], v[158:161], v[236:239], v[110:113]
	v_mfma_f32_16x16x32_bf16 v[106:109], v[138:141], v[244:247], v[106:109]
	v_mfma_f32_16x16x32_bf16 v[102:105], v[158:161], v[244:247], v[102:105]
	v_mfma_f32_16x16x32_bf16 v[98:101], v[178:181], v[216:219], v[98:101]
	v_mfma_f32_16x16x32_bf16 v[94:97], v[208:211], v[216:219], v[94:97]
	v_mfma_f32_16x16x32_bf16 v[90:93], v[178:181], v[224:227], v[90:93]
	v_mfma_f32_16x16x32_bf16 v[86:89], v[208:211], v[224:227], v[86:89]
	v_mfma_f32_16x16x32_bf16 v[82:85], v[178:181], v[232:235], v[82:85]
	v_mfma_f32_16x16x32_bf16 v[78:81], v[208:211], v[232:235], v[78:81]
	v_mfma_f32_16x16x32_bf16 v[74:77], v[178:181], v[240:243], v[74:77]
	v_mfma_f32_16x16x32_bf16 v[70:73], v[208:211], v[240:243], v[70:73]
	v_mfma_f32_16x16x32_bf16 v[98:101], v[204:207], v[220:223], v[98:101]
	v_mfma_f32_16x16x32_bf16 v[94:97], v[212:215], v[220:223], v[94:97]
	v_mfma_f32_16x16x32_bf16 v[90:93], v[204:207], v[228:231], v[90:93]
	v_mfma_f32_16x16x32_bf16 v[86:89], v[212:215], v[228:231], v[86:89]
	v_mfma_f32_16x16x32_bf16 v[82:85], v[204:207], v[236:239], v[82:85]
	v_mfma_f32_16x16x32_bf16 v[78:81], v[212:215], v[236:239], v[78:81]
	v_mfma_f32_16x16x32_bf16 v[74:77], v[204:207], v[244:247], v[74:77]
	v_mfma_f32_16x16x32_bf16 v[70:73], v[212:215], v[244:247], v[70:73]
	s_setprio 3
	s_barrier
	s_add_i32 s29, s31, s54
	s_mov_b32 m0, s29
	ds_read_b128 v[216:219], v177 offset:16384
	ds_read_b128 v[220:223], v177 offset:17408
	ds_read_b128 v[224:227], v177 offset:18432
	ds_read_b128 v[228:231], v177 offset:19456
	ds_read_b128 v[232:235], v177 offset:20480
	ds_read_b128 v[236:239], v177 offset:21504
	ds_read_b128 v[240:243], v177 offset:22528
	ds_read_b128 v[244:247], v177 offset:23552
	global_load_lds_dwordx4 v144, s[42:43]
	s_add_i32 m0, s29, 0x2000
	s_add_u32 s64, s42, 0x40000
	s_addc_u32 s65, s43, 0
	s_add_i32 s27, s27, s54
	global_load_lds_dwordx4 v148, s[42:43]
	s_mov_b32 m0, s27
	s_nop 0
	global_load_lds_dwordx4 v144, s[64:65]
	s_add_i32 m0, s27, 0x2000
	s_nop 0
	global_load_lds_dwordx4 v148, s[64:65]
	s_nop 0
	s_nop 0
	s_nop 0
	s_nop 0
	s_nop 0
	s_nop 0
	s_nop 0
	s_waitcnt vmcnt(6)
	s_waitcnt lgkmcnt(0)
	s_barrier
	s_setprio 0
	s_waitcnt lgkmcnt(0)
	v_mfma_f32_16x16x32_bf16 v[66:69], v[134:137], v[216:219], v[66:69]
	v_mfma_f32_16x16x32_bf16 v[62:65], v[154:157], v[216:219], v[62:65]
	v_mfma_f32_16x16x32_bf16 v[58:61], v[134:137], v[224:227], v[58:61]
	s_mov_b32 m0, s55
	v_mfma_f32_16x16x32_bf16 v[54:57], v[154:157], v[224:227], v[54:57]
	global_load_lds_dwordx4 v142, s[44:45]
	v_mfma_f32_16x16x32_bf16 v[50:53], v[134:137], v[232:235], v[50:53]
	v_mfma_f32_16x16x32_bf16 v[46:49], v[154:157], v[232:235], v[46:49]
	v_mfma_f32_16x16x32_bf16 v[42:45], v[134:137], v[240:243], v[42:45]
	v_mfma_f32_16x16x32_bf16 v[38:41], v[154:157], v[240:243], v[38:41]
	v_mfma_f32_16x16x32_bf16 v[66:69], v[138:141], v[220:223], v[66:69]
	v_mfma_f32_16x16x32_bf16 v[62:65], v[158:161], v[220:223], v[62:65]
	v_mfma_f32_16x16x32_bf16 v[58:61], v[138:141], v[228:231], v[58:61]
	s_mov_b32 m0, s56
	v_mfma_f32_16x16x32_bf16 v[54:57], v[158:161], v[228:231], v[54:57]
	global_load_lds_dwordx4 v146, s[44:45]
	v_mfma_f32_16x16x32_bf16 v[50:53], v[138:141], v[236:239], v[50:53]
	v_mfma_f32_16x16x32_bf16 v[46:49], v[158:161], v[236:239], v[46:49]
	v_mfma_f32_16x16x32_bf16 v[42:45], v[138:141], v[244:247], v[42:45]
	v_mfma_f32_16x16x32_bf16 v[38:41], v[158:161], v[244:247], v[38:41]
	v_mfma_f32_16x16x32_bf16 v[34:37], v[178:181], v[216:219], v[34:37]
	v_mfma_f32_16x16x32_bf16 v[30:33], v[208:211], v[216:219], v[30:33]
	v_mfma_f32_16x16x32_bf16 v[26:29], v[178:181], v[224:227], v[26:29]
	v_mfma_f32_16x16x32_bf16 v[22:25], v[208:211], v[224:227], v[22:25]
	v_mfma_f32_16x16x32_bf16 v[18:21], v[178:181], v[232:235], v[18:21]
	v_mfma_f32_16x16x32_bf16 v[14:17], v[208:211], v[232:235], v[14:17]
	v_mfma_f32_16x16x32_bf16 v[10:13], v[178:181], v[240:243], v[10:13]
	v_mfma_f32_16x16x32_bf16 v[4:7], v[208:211], v[240:243], v[6:9]
	v_mfma_f32_16x16x32_bf16 v[34:37], v[204:207], v[220:223], v[34:37]
	v_mfma_f32_16x16x32_bf16 v[30:33], v[212:215], v[220:223], v[30:33]
	v_mfma_f32_16x16x32_bf16 v[26:29], v[204:207], v[228:231], v[26:29]
	v_mfma_f32_16x16x32_bf16 v[22:25], v[212:215], v[228:231], v[22:25]
	v_mfma_f32_16x16x32_bf16 v[18:21], v[204:207], v[236:239], v[18:21]
	v_mfma_f32_16x16x32_bf16 v[14:17], v[212:215], v[236:239], v[14:17]
	v_mfma_f32_16x16x32_bf16 v[10:13], v[204:207], v[244:247], v[10:13]
	v_mfma_f32_16x16x32_bf16 v[4:7], v[212:215], v[244:247], v[4:7]
	s_setprio 3
	s_barrier
; #define PG8_STAGE(bufoff, gbase, voff) do { _Pragma("unroll") for (int _i = 0; _i < 2; ++_i) \
;         __builtin_amdgcn_global_load_lds((const unsigned*)((const char*)(gbase) + (voff)[_i]), (PG8_LAS unsigned*)(lds + (bufoff) + ldsw + _i * 8192), 16, 0, 0); } while (0)
; #define PG8_LDA(dst, b, h) do { _Pragma("unroll") for (int m = 0; m < 4; ++m) _Pragma("unroll") for (int k = 0; k < 2; ++k) dst[m][k] = *(const PG8_LAS bf16x8*)(lds + PG8_SA(b, h) + aoff + m * 2048 + k * 1024); } while (0)
; #define PG8_LDB(dst, b, h) do { _Pragma("unroll") for (int n = 0; n < 2; ++n) _Pragma("unroll") for (int k = 0; k < 2; ++k) dst[n][k] = *(const PG8_LAS bf16x8*)(lds + PG8_SB(b, h) + boff + n * 2048 + k * 1024); } while (0)
; #define PG8_MMA(ai, bj, At, Bt) do { __builtin_amdgcn_s_setprio(1); _Pragma("unroll") for (int m = 0; m < 4; ++m) _Pragma("unroll") for (int n = 0; n < 2; ++n) _Pragma("unroll") for (int k = 0; k < 2; ++k) \
;         acc[ai][bj][m][n] = __builtin_amdgcn_mfma_f32_16x16x32_bf16(Bt[n][k], At[m][k], acc[ai][bj][m][n], 0, 0, 0); __builtin_amdgcn_s_setprio(0); } while (0)
; #define PG8_WAIT_V(n) asm volatile("s_waitcnt vmcnt(" #n ")" ::: "memory")
; #define PG8_WAIT_L(n) asm volatile("s_waitcnt lgkmcnt(" #n ")" ::: "memory")
; #define PG8_BAR __builtin_amdgcn_s_barrier()
; #define PG8_SCHED __builtin_amdgcn_sched_barrier(0)
; template <class Epi, class Sched, bool ALIGN_EPI = false, bool SP2 = false>
; __device__ __forceinline__ void gemm_phase(PG8_LAS unsigned char* lds, const Gemm g, const Sched& S, const Epi& E) {
;     ...
;             PG8_LDB(B0, 1, 0); PG8_LDB(B1, 1, 1); PG8_SCHED; PG8_LDA(At, 1, 0); PG8_STAGE(PG8_SA(0, 1), a2 + hstep, voffA);
;             PG8_WAIT_V(8); PG8_WAIT_L(0); PG8_BAR; PG8_MMA(0, 0, At, B0); PG8_MMA(0, 1, At, B1); PG8_BAR; PG8_SCHED;
;             PG8_LDA(At, 1, 1); PG8_STAGE(PG8_SB(1, 0), b3, voffB); PG8_STAGE(PG8_SB(1, 1), b3 + hstep, voffB); PG8_STAGE(PG8_SA(1, 0), a3, voffA);
;             PG8_WAIT_V(8); PG8_WAIT_L(0); PG8_BAR; PG8_MMA(1, 0, At, B0); PG8_MMA(1, 1, At, B1); PG8_BAR; PG8_SCHED;
	s_add_i32 s27, 0, 0x18000
	v_add_u32_e32 v2, s27, v173
	s_add_i32 s29, 0, 0x1c000
	ds_read_b128 v[134:137], v2
	ds_read_b128 v[138:141], v2 offset:1024
	ds_read_b128 v[154:157], v2 offset:2048
	ds_read_b128 v[158:161], v2 offset:3072
	v_add_u32_e32 v2, s29, v173
	ds_read_b128 v[178:181], v2
	ds_read_b128 v[204:207], v2 offset:1024
	ds_read_b128 v[208:211], v2 offset:2048
	ds_read_b128 v[212:215], v2 offset:3072
	s_add_u32 s100, s44, 0x80
	s_addc_u32 s101, s45, 0
	s_add_u32 s44, s44, 0x40000
	s_addc_u32 s45, s45, 0
	s_mov_b32 m0, s57
	ds_read_b128 v[216:219], v177 offset:32768
	ds_read_b128 v[220:223], v177 offset:33792
	ds_read_b128 v[224:227], v177 offset:34816
	ds_read_b128 v[228:231], v177 offset:35840
	ds_read_b128 v[232:235], v177 offset:36864
	ds_read_b128 v[236:239], v177 offset:37888
	ds_read_b128 v[240:243], v177 offset:38912
	ds_read_b128 v[244:247], v177 offset:39936
	global_load_lds_dwordx4 v142, s[44:45]
	s_waitcnt vmcnt(7)
	s_waitcnt lgkmcnt(0)
	s_barrier
	s_setprio 0
	s_waitcnt lgkmcnt(0)
	v_mfma_f32_16x16x32_bf16 v[130:133], v[134:137], v[216:219], v[130:133]
	v_mfma_f32_16x16x32_bf16 v[126:129], v[154:157], v[216:219], v[126:129]
	v_mfma_f32_16x16x32_bf16 v[122:125], v[134:137], v[224:227], v[122:125]
	s_mov_b32 m0, s58
	v_mfma_f32_16x16x32_bf16 v[118:121], v[154:157], v[224:227], v[118:121]
	global_load_lds_dwordx4 v146, s[44:45]
	v_mfma_f32_16x16x32_bf16 v[114:117], v[134:137], v[232:235], v[114:117]
	v_mfma_f32_16x16x32_bf16 v[110:113], v[154:157], v[232:235], v[110:113]
	v_mfma_f32_16x16x32_bf16 v[106:109], v[134:137], v[240:243], v[106:109]
	v_mfma_f32_16x16x32_bf16 v[102:105], v[154:157], v[240:243], v[102:105]
	v_mfma_f32_16x16x32_bf16 v[130:133], v[138:141], v[220:223], v[130:133]
	v_mfma_f32_16x16x32_bf16 v[126:129], v[158:161], v[220:223], v[126:129]
	v_mfma_f32_16x16x32_bf16 v[122:125], v[138:141], v[228:231], v[122:125]
	v_mfma_f32_16x16x32_bf16 v[118:121], v[158:161], v[228:231], v[118:121]
	v_mfma_f32_16x16x32_bf16 v[114:117], v[138:141], v[236:239], v[114:117]
	v_mfma_f32_16x16x32_bf16 v[110:113], v[158:161], v[236:239], v[110:113]
	v_mfma_f32_16x16x32_bf16 v[106:109], v[138:141], v[244:247], v[106:109]
	v_mfma_f32_16x16x32_bf16 v[102:105], v[158:161], v[244:247], v[102:105]
	v_mfma_f32_16x16x32_bf16 v[98:101], v[178:181], v[216:219], v[98:101]
	v_mfma_f32_16x16x32_bf16 v[94:97], v[208:211], v[216:219], v[94:97]
	v_mfma_f32_16x16x32_bf16 v[90:93], v[178:181], v[224:227], v[90:93]
	v_mfma_f32_16x16x32_bf16 v[86:89], v[208:211], v[224:227], v[86:89]
	v_mfma_f32_16x16x32_bf16 v[82:85], v[178:181], v[232:235], v[82:85]
	v_mfma_f32_16x16x32_bf16 v[78:81], v[208:211], v[232:235], v[78:81]
	v_mfma_f32_16x16x32_bf16 v[74:77], v[178:181], v[240:243], v[74:77]
	v_mfma_f32_16x16x32_bf16 v[70:73], v[208:211], v[240:243], v[70:73]
	v_mfma_f32_16x16x32_bf16 v[98:101], v[204:207], v[220:223], v[98:101]
	v_mfma_f32_16x16x32_bf16 v[94:97], v[212:215], v[220:223], v[94:97]
	v_mfma_f32_16x16x32_bf16 v[90:93], v[204:207], v[228:231], v[90:93]
	v_mfma_f32_16x16x32_bf16 v[86:89], v[212:215], v[228:231], v[86:89]
	v_mfma_f32_16x16x32_bf16 v[82:85], v[204:207], v[236:239], v[82:85]
	v_mfma_f32_16x16x32_bf16 v[78:81], v[212:215], v[236:239], v[78:81]
	v_mfma_f32_16x16x32_bf16 v[74:77], v[204:207], v[244:247], v[74:77]
	v_mfma_f32_16x16x32_bf16 v[70:73], v[212:215], v[244:247], v[70:73]
	s_setprio 3
	s_barrier
	s_add_i32 s27, s27, s54
	s_add_i32 m0, s27, 0xffffff80
	ds_read_b128 v[216:219], v177 offset:49152
	ds_read_b128 v[220:223], v177 offset:50176
	ds_read_b128 v[224:227], v177 offset:51200
	ds_read_b128 v[228:231], v177 offset:52224
	ds_read_b128 v[232:235], v177 offset:53248
	ds_read_b128 v[236:239], v177 offset:54272
	ds_read_b128 v[240:243], v177 offset:55296
	ds_read_b128 v[244:247], v177 offset:56320
	global_load_lds_dwordx4 v144, s[42:43] offset:128
	s_add_i32 m0, s27, 0x1f80
	s_add_i32 s27, s29, s54
	global_load_lds_dwordx4 v148, s[42:43] offset:128
	s_add_u32 s42, s42, 0x40080
	s_addc_u32 s43, s43, 0
	s_mov_b32 m0, s27
	s_nop 0
	global_load_lds_dwordx4 v144, s[42:43]
	s_add_i32 m0, s27, 0x2000
	s_nop 0
	global_load_lds_dwordx4 v148, s[42:43]
	s_waitcnt vmcnt(6)
	s_waitcnt lgkmcnt(0)
	s_barrier
	s_setprio 0
	s_waitcnt lgkmcnt(0)
	v_mfma_f32_16x16x32_bf16 v[66:69], v[134:137], v[216:219], v[66:69]
	v_mfma_f32_16x16x32_bf16 v[62:65], v[154:157], v[216:219], v[62:65]
	v_mfma_f32_16x16x32_bf16 v[58:61], v[134:137], v[224:227], v[58:61]
	s_mov_b32 m0, s61
	v_mfma_f32_16x16x32_bf16 v[54:57], v[154:157], v[224:227], v[54:57]
	global_load_lds_dwordx4 v142, s[100:101]
	v_mfma_f32_16x16x32_bf16 v[50:53], v[134:137], v[232:235], v[50:53]
	v_mfma_f32_16x16x32_bf16 v[46:49], v[154:157], v[232:235], v[46:49]
	v_mfma_f32_16x16x32_bf16 v[42:45], v[134:137], v[240:243], v[42:45]
	v_mfma_f32_16x16x32_bf16 v[38:41], v[154:157], v[240:243], v[38:41]
	v_mfma_f32_16x16x32_bf16 v[66:69], v[138:141], v[220:223], v[66:69]
	v_mfma_f32_16x16x32_bf16 v[62:65], v[158:161], v[220:223], v[62:65]
	v_mfma_f32_16x16x32_bf16 v[58:61], v[138:141], v[228:231], v[58:61]
	s_mov_b32 m0, s62
	v_mfma_f32_16x16x32_bf16 v[54:57], v[158:161], v[228:231], v[54:57]
	global_load_lds_dwordx4 v146, s[100:101]
	v_mfma_f32_16x16x32_bf16 v[50:53], v[138:141], v[236:239], v[50:53]
	v_mfma_f32_16x16x32_bf16 v[46:49], v[158:161], v[236:239], v[46:49]
	v_mfma_f32_16x16x32_bf16 v[42:45], v[138:141], v[244:247], v[42:45]
	v_mfma_f32_16x16x32_bf16 v[38:41], v[158:161], v[244:247], v[38:41]
	v_mfma_f32_16x16x32_bf16 v[34:37], v[178:181], v[216:219], v[34:37]
	v_mfma_f32_16x16x32_bf16 v[30:33], v[208:211], v[216:219], v[30:33]
	v_mfma_f32_16x16x32_bf16 v[26:29], v[178:181], v[224:227], v[26:29]
	v_mfma_f32_16x16x32_bf16 v[22:25], v[208:211], v[224:227], v[22:25]
	v_mfma_f32_16x16x32_bf16 v[18:21], v[178:181], v[232:235], v[18:21]
	v_mfma_f32_16x16x32_bf16 v[14:17], v[208:211], v[232:235], v[14:17]
	v_mfma_f32_16x16x32_bf16 v[8:11], v[178:181], v[240:243], v[10:13]
	v_mfma_f32_16x16x32_bf16 v[4:7], v[208:211], v[240:243], v[4:7]
	v_mfma_f32_16x16x32_bf16 v[34:37], v[204:207], v[220:223], v[34:37]
	v_mfma_f32_16x16x32_bf16 v[30:33], v[212:215], v[220:223], v[30:33]
	v_mfma_f32_16x16x32_bf16 v[26:29], v[204:207], v[228:231], v[26:29]
	v_mfma_f32_16x16x32_bf16 v[22:25], v[212:215], v[228:231], v[22:25]
	v_mfma_f32_16x16x32_bf16 v[18:21], v[204:207], v[236:239], v[18:21]
	v_mfma_f32_16x16x32_bf16 v[14:17], v[212:215], v[236:239], v[14:17]
	v_mfma_f32_16x16x32_bf16 v[10:13], v[204:207], v[244:247], v[8:11]
	v_mfma_f32_16x16x32_bf16 v[6:9], v[212:215], v[244:247], v[4:7]
	s_setprio 3
	s_barrier
	s_add_i32 s26, s26, 2
	s_add_u32 s40, s40, 0x100
	s_addc_u32 s41, s41, 0
	s_add_u32 s11, s11, 0x100
	s_addc_u32 s13, s13, 0
	s_cmp_gt_u32 s26, 13
	s_cbranch_scc0 .LBB0_2096
	s_and_b64 vcc, exec, s[8:9]
	s_cbranch_vccz .LBB0_2099
	s_barrier

; #define PG8_STAGE(bufoff, gbase, voff) do { _Pragma("unroll") for (int _i = 0; _i < 2; ++_i) \
;         __builtin_amdgcn_global_load_lds((const unsigned*)((const char*)(gbase) + (voff)[_i]), (PG8_LAS unsigned*)(lds + (bufoff) + ldsw + _i * 8192), 16, 0, 0); } while (0)
; #define PG8_LDA(dst, b, h) do { _Pragma("unroll") for (int m = 0; m < 4; ++m) _Pragma("unroll") for (int k = 0; k < 2; ++k) dst[m][k] = *(const PG8_LAS bf16x8*)(lds + PG8_SA(b, h) + aoff + m * 2048 + k * 1024); } while (0)
; #define PG8_LDB(dst, b, h) do { _Pragma("unroll") for (int n = 0; n < 2; ++n) _Pragma("unroll") for (int k = 0; k < 2; ++k) dst[n][k] = *(const PG8_LAS bf16x8*)(lds + PG8_SB(b, h) + boff + n * 2048 + k * 1024); } while (0)
; #define PG8_MMA(ai, bj, At, Bt) do { __builtin_amdgcn_s_setprio(1); _Pragma("unroll") for (int m = 0; m < 4; ++m) _Pragma("unroll") for (int n = 0; n < 2; ++n) _Pragma("unroll") for (int k = 0; k < 2; ++k) \
;         acc[ai][bj][m][n] = __builtin_amdgcn_mfma_f32_16x16x32_bf16(Bt[n][k], At[m][k], acc[ai][bj][m][n], 0, 0, 0); __builtin_amdgcn_s_setprio(0); } while (0)
; #define PG8_WAIT_V(n) asm volatile("s_waitcnt vmcnt(" #n ")" ::: "memory")
; #define PG8_WAIT_L(n) asm volatile("s_waitcnt lgkmcnt(" #n ")" ::: "memory")
; template <class Epi, class Sched, bool ALIGN_EPI = false, bool SP2 = false>
; __device__ __forceinline__ void gemm_phase(PG8_LAS unsigned char* lds, const Gemm g, const Sched& S, const Epi& E) {
;     ...
;             const bool last = (t == nt - 2);
;             const char* a1 = cA + (size_t)(t + 1) * kstep;
;             const char* a2 = last ? nA : cA + (size_t)(t + 2) * kstep; const char* b2 = last ? nB : cB + (size_t)(t + 2) * kstep;
;             const char* a3 = a2 + kstep; const char* b3 = b2 + kstep;
;             if (last && has_next) S.a_ready(nxt);
;             if constexpr (SP2) {
;             PG8_LDB(B0, 0, 0); PG8_LDB(B1, 0, 1); PG8_SCHED; PG8_LDA(At, 0, 0); PG8_STAGE(PG8_SA(1, 1), a1 + hstep, voffA);
;             PG8_WAIT_V(8); PG8_WAIT_L(0); PG8_BAR; PG8_MMA(0, 0, At, B0); PG8_MMA(0, 1, At, B1); PG8_BAR; PG8_SCHED;
;             PG8_LDA(At, 0, 1); PG8_STAGE(PG8_SB(0, 0), b2, voffB); PG8_STAGE(PG8_SB(0, 1), b2 + hstep, voffB); PG8_STAGE(PG8_SA(0, 0), a2, voffA);
;             PG8_WAIT_V(8); PG8_WAIT_L(0); PG8_BAR; PG8_MMA(1, 0, At, B0); PG8_MMA(1, 1, At, B1); PG8_BAR; PG8_SCHED;
.LBB0_2185:
	s_add_u32 s42, s40, 0x100
	s_addc_u32 s43, s41, 0
	s_add_i32 s37, 0, 0x10000
	s_cmp_eq_u32 s31, 28
	s_cselect_b32 s47, s5, s43
	s_cselect_b32 s46, s4, s42
	v_add_u32_e32 v135, s37, v173
	s_cselect_b32 s45, s35, s29
	s_cselect_b32 s44, s34, s2
	s_add_i32 s39, 0, 0x14000
	ds_read_b128 v[142:145], v135
	ds_read_b128 v[146:149], v135 offset:1024
	ds_read_b128 v[150:153], v135 offset:2048
	ds_read_b128 v[154:157], v135 offset:3072
	v_add_u32_e32 v135, s39, v173
	ds_read_b128 v[158:161], v135
	ds_read_b128 v[174:177], v135 offset:1024
	ds_read_b128 v[180:183], v135 offset:2048
	ds_read_b128 v[204:207], v135 offset:3072
	v_lshl_add_u64 v[162:163], s[40:41], 0, v[138:139]
	s_add_i32 m0, s55, 0xc000
	ds_read_b128 v[208:211], v179
	ds_read_b128 v[212:215], v179 offset:1024
	ds_read_b128 v[216:219], v179 offset:2048
	ds_read_b128 v[220:223], v179 offset:3072
	ds_read_b128 v[224:227], v179 offset:4096
	ds_read_b128 v[228:231], v179 offset:5120
	ds_read_b128 v[232:235], v179 offset:6144
	ds_read_b128 v[236:239], v179 offset:7168
	global_load_lds_dwordx4 v[162:163], off
	v_lshl_add_u64 v[162:163], s[40:41], 0, v[140:141]
	s_nop 0
	s_waitcnt vmcnt(7)
	s_waitcnt lgkmcnt(0)
	s_barrier
	s_setprio 0
	s_waitcnt lgkmcnt(0)
	v_mfma_f32_16x16x32_bf16 v[128:131], v[142:145], v[208:211], v[128:131]
	v_mfma_f32_16x16x32_bf16 v[124:127], v[150:153], v[208:211], v[124:127]
	v_mfma_f32_16x16x32_bf16 v[112:115], v[142:145], v[216:219], v[112:115]
	s_add_i32 m0, s55, 0xe000
	v_mfma_f32_16x16x32_bf16 v[108:111], v[150:153], v[216:219], v[108:111]
	global_load_lds_dwordx4 v[162:163], off
	v_mfma_f32_16x16x32_bf16 v[96:99], v[142:145], v[224:227], v[96:99]
	v_mfma_f32_16x16x32_bf16 v[92:95], v[150:153], v[224:227], v[92:95]
	v_mfma_f32_16x16x32_bf16 v[80:83], v[142:145], v[232:235], v[80:83]
	v_mfma_f32_16x16x32_bf16 v[76:79], v[150:153], v[232:235], v[76:79]
	v_mfma_f32_16x16x32_bf16 v[128:131], v[146:149], v[212:215], v[128:131]
	v_mfma_f32_16x16x32_bf16 v[124:127], v[154:157], v[212:215], v[124:127]
	v_mfma_f32_16x16x32_bf16 v[112:115], v[146:149], v[220:223], v[112:115]
	v_mfma_f32_16x16x32_bf16 v[108:111], v[154:157], v[220:223], v[108:111]
	v_mfma_f32_16x16x32_bf16 v[96:99], v[146:149], v[228:231], v[96:99]
	v_mfma_f32_16x16x32_bf16 v[92:95], v[154:157], v[228:231], v[92:95]
	v_mfma_f32_16x16x32_bf16 v[80:83], v[146:149], v[236:239], v[80:83]
	v_mfma_f32_16x16x32_bf16 v[76:79], v[154:157], v[236:239], v[76:79]
	v_mfma_f32_16x16x32_bf16 v[120:123], v[158:161], v[208:211], v[120:123]
	v_mfma_f32_16x16x32_bf16 v[116:119], v[180:183], v[208:211], v[116:119]
	v_mfma_f32_16x16x32_bf16 v[104:107], v[158:161], v[216:219], v[104:107]
	v_mfma_f32_16x16x32_bf16 v[100:103], v[180:183], v[216:219], v[100:103]
	v_mfma_f32_16x16x32_bf16 v[88:91], v[158:161], v[224:227], v[88:91]
	v_mfma_f32_16x16x32_bf16 v[84:87], v[180:183], v[224:227], v[84:87]
	v_mfma_f32_16x16x32_bf16 v[72:75], v[158:161], v[232:235], v[72:75]
	v_mfma_f32_16x16x32_bf16 v[68:71], v[180:183], v[232:235], v[68:71]
	v_mfma_f32_16x16x32_bf16 v[120:123], v[174:177], v[212:215], v[120:123]
	v_mfma_f32_16x16x32_bf16 v[116:119], v[204:207], v[212:215], v[116:119]
	v_mfma_f32_16x16x32_bf16 v[104:107], v[174:177], v[220:223], v[104:107]
	v_mfma_f32_16x16x32_bf16 v[100:103], v[204:207], v[220:223], v[100:103]
	v_mfma_f32_16x16x32_bf16 v[88:91], v[174:177], v[228:231], v[88:91]
	v_mfma_f32_16x16x32_bf16 v[84:87], v[204:207], v[228:231], v[84:87]
	v_mfma_f32_16x16x32_bf16 v[72:75], v[174:177], v[236:239], v[72:75]
	v_mfma_f32_16x16x32_bf16 v[68:71], v[204:207], v[236:239], v[68:71]
	s_setprio 3
	s_barrier
	s_add_i32 s37, s37, s54
	s_mov_b32 m0, s37
	ds_read_b128 v[208:211], v179 offset:16384
	ds_read_b128 v[212:215], v179 offset:17408
	ds_read_b128 v[216:219], v179 offset:18432
	ds_read_b128 v[220:223], v179 offset:19456
	ds_read_b128 v[224:227], v179 offset:20480
	ds_read_b128 v[228:231], v179 offset:21504
	ds_read_b128 v[232:235], v179 offset:22528
	ds_read_b128 v[236:239], v179 offset:23552
	global_load_lds_dwordx4 v2, s[44:45]
	s_add_i32 m0, s37, 0x2000
	s_add_u32 s40, s44, 0x80000
	s_addc_u32 s41, s45, 0
	s_add_i32 s37, s39, s54
	global_load_lds_dwordx4 v132, s[44:45]
	s_mov_b32 m0, s37
	s_nop 0
	global_load_lds_dwordx4 v2, s[40:41]
	s_add_i32 m0, s37, 0x2000
	s_nop 0
	global_load_lds_dwordx4 v132, s[40:41]
	s_nop 0
	s_nop 0
	s_nop 0
	s_nop 0
	s_nop 0
	s_nop 0
	s_nop 0
	s_waitcnt vmcnt(6)
	s_waitcnt lgkmcnt(0)
	s_barrier
	s_setprio 0
	s_waitcnt lgkmcnt(0)
	v_mfma_f32_16x16x32_bf16 v[64:67], v[142:145], v[208:211], v[64:67]
	v_mfma_f32_16x16x32_bf16 v[60:63], v[150:153], v[208:211], v[60:63]
	v_mfma_f32_16x16x32_bf16 v[48:51], v[142:145], v[216:219], v[48:51]
	s_mov_b32 m0, s55
	v_mfma_f32_16x16x32_bf16 v[44:47], v[150:153], v[216:219], v[44:47]
	global_load_lds_dwordx4 v2, s[46:47]
	v_mfma_f32_16x16x32_bf16 v[32:35], v[142:145], v[224:227], v[32:35]
	v_mfma_f32_16x16x32_bf16 v[28:31], v[150:153], v[224:227], v[28:31]
	v_mfma_f32_16x16x32_bf16 v[16:19], v[142:145], v[232:235], v[16:19]
	v_mfma_f32_16x16x32_bf16 v[12:15], v[150:153], v[232:235], v[12:15]
	v_mfma_f32_16x16x32_bf16 v[64:67], v[146:149], v[212:215], v[64:67]
	v_mfma_f32_16x16x32_bf16 v[60:63], v[154:157], v[212:215], v[60:63]
	v_mfma_f32_16x16x32_bf16 v[48:51], v[146:149], v[220:223], v[48:51]
	s_mov_b32 m0, s56
	v_mfma_f32_16x16x32_bf16 v[44:47], v[154:157], v[220:223], v[44:47]
	global_load_lds_dwordx4 v132, s[46:47]
	v_mfma_f32_16x16x32_bf16 v[32:35], v[146:149], v[228:231], v[32:35]
	v_mfma_f32_16x16x32_bf16 v[28:31], v[154:157], v[228:231], v[28:31]
	v_mfma_f32_16x16x32_bf16 v[16:19], v[146:149], v[236:239], v[16:19]
	v_mfma_f32_16x16x32_bf16 v[12:15], v[154:157], v[236:239], v[12:15]
	v_mfma_f32_16x16x32_bf16 v[56:59], v[158:161], v[208:211], v[56:59]
	v_mfma_f32_16x16x32_bf16 v[52:55], v[180:183], v[208:211], v[52:55]
	v_mfma_f32_16x16x32_bf16 v[40:43], v[158:161], v[216:219], v[40:43]
	v_mfma_f32_16x16x32_bf16 v[36:39], v[180:183], v[216:219], v[36:39]
	v_mfma_f32_16x16x32_bf16 v[24:27], v[158:161], v[224:227], v[24:27]
	v_mfma_f32_16x16x32_bf16 v[20:23], v[180:183], v[224:227], v[20:23]
	v_mfma_f32_16x16x32_bf16 v[8:11], v[158:161], v[232:235], v[8:11]
	v_mfma_f32_16x16x32_bf16 v[4:7], v[180:183], v[232:235], v[4:7]
	v_mfma_f32_16x16x32_bf16 v[56:59], v[174:177], v[212:215], v[56:59]
	v_mfma_f32_16x16x32_bf16 v[52:55], v[204:207], v[212:215], v[52:55]
	v_mfma_f32_16x16x32_bf16 v[40:43], v[174:177], v[220:223], v[40:43]
	v_mfma_f32_16x16x32_bf16 v[36:39], v[204:207], v[220:223], v[36:39]
	v_mfma_f32_16x16x32_bf16 v[24:27], v[174:177], v[228:231], v[24:27]
	v_mfma_f32_16x16x32_bf16 v[20:23], v[204:207], v[228:231], v[20:23]
	v_mfma_f32_16x16x32_bf16 v[8:11], v[174:177], v[236:239], v[8:11]
	v_mfma_f32_16x16x32_bf16 v[4:7], v[204:207], v[236:239], v[4:7]
	s_setprio 3
	s_barrier
; #define PG8_STAGE(bufoff, gbase, voff) do { _Pragma("unroll") for (int _i = 0; _i < 2; ++_i) \
;         __builtin_amdgcn_global_load_lds((const unsigned*)((const char*)(gbase) + (voff)[_i]), (PG8_LAS unsigned*)(lds + (bufoff) + ldsw + _i * 8192), 16, 0, 0); } while (0)
; #define PG8_LDA(dst, b, h) do { _Pragma("unroll") for (int m = 0; m < 4; ++m) _Pragma("unroll") for (int k = 0; k < 2; ++k) dst[m][k] = *(const PG8_LAS bf16x8*)(lds + PG8_SA(b, h) + aoff + m * 2048 + k * 1024); } while (0)
; #define PG8_LDB(dst, b, h) do { _Pragma("unroll") for (int n = 0; n < 2; ++n) _Pragma("unroll") for (int k = 0; k < 2; ++k) dst[n][k] = *(const PG8_LAS bf16x8*)(lds + PG8_SB(b, h) + boff + n * 2048 + k * 1024); } while (0)
; #define PG8_MMA(ai, bj, At, Bt) do { __builtin_amdgcn_s_setprio(1); _Pragma("unroll") for (int m = 0; m < 4; ++m) _Pragma("unroll") for (int n = 0; n < 2; ++n) _Pragma("unroll") for (int k = 0; k < 2; ++k) \
;         acc[ai][bj][m][n] = __builtin_amdgcn_mfma_f32_16x16x32_bf16(Bt[n][k], At[m][k], acc[ai][bj][m][n], 0, 0, 0); __builtin_amdgcn_s_setprio(0); } while (0)
; #define PG8_WAIT_V(n) asm volatile("s_waitcnt vmcnt(" #n ")" ::: "memory")
; #define PG8_WAIT_L(n) asm volatile("s_waitcnt lgkmcnt(" #n ")" ::: "memory")
; #define PG8_BAR __builtin_amdgcn_s_barrier()
; #define PG8_SCHED __builtin_amdgcn_sched_barrier(0)
; template <class Epi, class Sched, bool ALIGN_EPI = false, bool SP2 = false>
; __device__ __forceinline__ void gemm_phase(PG8_LAS unsigned char* lds, const Gemm g, const Sched& S, const Epi& E) {
;     ...
;             PG8_LDB(B0, 1, 0); PG8_LDB(B1, 1, 1); PG8_SCHED; PG8_LDA(At, 1, 0); PG8_STAGE(PG8_SA(0, 1), a2 + hstep, voffA);
;             PG8_WAIT_V(8); PG8_WAIT_L(0); PG8_BAR; PG8_MMA(0, 0, At, B0); PG8_MMA(0, 1, At, B1); PG8_BAR; PG8_SCHED;
;             PG8_LDA(At, 1, 1); PG8_STAGE(PG8_SB(1, 0), b3, voffB); PG8_STAGE(PG8_SB(1, 1), b3 + hstep, voffB); PG8_STAGE(PG8_SA(1, 0), a3, voffA);
;             PG8_WAIT_V(8); PG8_WAIT_L(0); PG8_BAR; PG8_MMA(1, 0, At, B0); PG8_MMA(1, 1, At, B1); PG8_BAR; PG8_SCHED;
	s_add_i32 s37, 0, 0x18000
	v_add_u32_e32 v135, s37, v173
	s_add_i32 s39, 0, 0x1c000
	ds_read_b128 v[142:145], v135
	ds_read_b128 v[146:149], v135 offset:1024
	ds_read_b128 v[150:153], v135 offset:2048
	ds_read_b128 v[154:157], v135 offset:3072
	v_add_u32_e32 v135, s39, v173
	ds_read_b128 v[158:161], v135
	ds_read_b128 v[174:177], v135 offset:1024
	ds_read_b128 v[180:183], v135 offset:2048
	ds_read_b128 v[204:207], v135 offset:3072
	s_add_u32 s40, s46, 0x80000
	s_addc_u32 s41, s47, 0
	s_mov_b32 m0, s57
	ds_read_b128 v[208:211], v179 offset:32768
	ds_read_b128 v[212:215], v179 offset:33792
	ds_read_b128 v[216:219], v179 offset:34816
	ds_read_b128 v[220:223], v179 offset:35840
	ds_read_b128 v[224:227], v179 offset:36864
	ds_read_b128 v[228:231], v179 offset:37888
	ds_read_b128 v[232:235], v179 offset:38912
	ds_read_b128 v[236:239], v179 offset:39936
	global_load_lds_dwordx4 v2, s[40:41]
	s_waitcnt vmcnt(7)
	s_waitcnt lgkmcnt(0)
	s_barrier
	s_setprio 0
	s_waitcnt lgkmcnt(0)
	v_mfma_f32_16x16x32_bf16 v[128:131], v[142:145], v[208:211], v[128:131]
	v_mfma_f32_16x16x32_bf16 v[124:127], v[150:153], v[208:211], v[124:127]
	v_mfma_f32_16x16x32_bf16 v[112:115], v[142:145], v[216:219], v[112:115]
	s_mov_b32 m0, s58
	v_mfma_f32_16x16x32_bf16 v[108:111], v[150:153], v[216:219], v[108:111]
	global_load_lds_dwordx4 v132, s[40:41]
	v_mfma_f32_16x16x32_bf16 v[96:99], v[142:145], v[224:227], v[96:99]
	v_mfma_f32_16x16x32_bf16 v[92:95], v[150:153], v[224:227], v[92:95]
	v_mfma_f32_16x16x32_bf16 v[80:83], v[142:145], v[232:235], v[80:83]
	v_mfma_f32_16x16x32_bf16 v[76:79], v[150:153], v[232:235], v[76:79]
	v_mfma_f32_16x16x32_bf16 v[128:131], v[146:149], v[212:215], v[128:131]
	v_mfma_f32_16x16x32_bf16 v[124:127], v[154:157], v[212:215], v[124:127]
	v_mfma_f32_16x16x32_bf16 v[112:115], v[146:149], v[220:223], v[112:115]
	v_mfma_f32_16x16x32_bf16 v[108:111], v[154:157], v[220:223], v[108:111]
	v_mfma_f32_16x16x32_bf16 v[96:99], v[146:149], v[228:231], v[96:99]
	v_mfma_f32_16x16x32_bf16 v[92:95], v[154:157], v[228:231], v[92:95]
	v_mfma_f32_16x16x32_bf16 v[80:83], v[146:149], v[236:239], v[80:83]
	v_mfma_f32_16x16x32_bf16 v[76:79], v[154:157], v[236:239], v[76:79]
	v_mfma_f32_16x16x32_bf16 v[120:123], v[158:161], v[208:211], v[120:123]
	v_mfma_f32_16x16x32_bf16 v[116:119], v[180:183], v[208:211], v[116:119]
	v_mfma_f32_16x16x32_bf16 v[104:107], v[158:161], v[216:219], v[104:107]
	v_mfma_f32_16x16x32_bf16 v[100:103], v[180:183], v[216:219], v[100:103]
	v_mfma_f32_16x16x32_bf16 v[88:91], v[158:161], v[224:227], v[88:91]
	v_mfma_f32_16x16x32_bf16 v[84:87], v[180:183], v[224:227], v[84:87]
	v_mfma_f32_16x16x32_bf16 v[72:75], v[158:161], v[232:235], v[72:75]
	v_mfma_f32_16x16x32_bf16 v[68:71], v[180:183], v[232:235], v[68:71]
	v_mfma_f32_16x16x32_bf16 v[120:123], v[174:177], v[212:215], v[120:123]
	v_mfma_f32_16x16x32_bf16 v[116:119], v[204:207], v[212:215], v[116:119]
	v_mfma_f32_16x16x32_bf16 v[104:107], v[174:177], v[220:223], v[104:107]
	v_mfma_f32_16x16x32_bf16 v[100:103], v[204:207], v[220:223], v[100:103]
	v_mfma_f32_16x16x32_bf16 v[88:91], v[174:177], v[228:231], v[88:91]
	v_mfma_f32_16x16x32_bf16 v[84:87], v[204:207], v[228:231], v[84:87]
	v_mfma_f32_16x16x32_bf16 v[72:75], v[174:177], v[236:239], v[72:75]
	v_mfma_f32_16x16x32_bf16 v[68:71], v[204:207], v[236:239], v[68:71]
	s_setprio 3
	s_barrier
	s_add_i32 s37, s37, s54
	s_add_i32 m0, s37, 0xffffff80
	ds_read_b128 v[208:211], v179 offset:49152
	ds_read_b128 v[212:215], v179 offset:50176
	ds_read_b128 v[216:219], v179 offset:51200
	ds_read_b128 v[220:223], v179 offset:52224
	ds_read_b128 v[224:227], v179 offset:53248
	ds_read_b128 v[228:231], v179 offset:54272
	ds_read_b128 v[232:235], v179 offset:55296
	ds_read_b128 v[236:239], v179 offset:56320
	global_load_lds_dwordx4 v2, s[44:45] offset:128
	s_add_i32 m0, s37, 0x1f80
	s_add_u32 s40, s44, 0x80080
	s_addc_u32 s41, s45, 0
	s_add_i32 s37, s39, s54
	global_load_lds_dwordx4 v132, s[44:45] offset:128
	s_mov_b32 m0, s37
	s_nop 0
	global_load_lds_dwordx4 v2, s[40:41]
	s_add_i32 m0, s37, 0x2000
	s_nop 0
	global_load_lds_dwordx4 v132, s[40:41]
	s_waitcnt vmcnt(6)
	s_waitcnt lgkmcnt(0)
	s_barrier
	s_setprio 0
	s_waitcnt lgkmcnt(0)
	v_mfma_f32_16x16x32_bf16 v[64:67], v[142:145], v[208:211], v[64:67]
	v_mfma_f32_16x16x32_bf16 v[60:63], v[150:153], v[208:211], v[60:63]
	v_mfma_f32_16x16x32_bf16 v[48:51], v[142:145], v[216:219], v[48:51]
	s_add_i32 m0, s60, 0xffffff80
	v_mfma_f32_16x16x32_bf16 v[44:47], v[150:153], v[216:219], v[44:47]
	global_load_lds_dwordx4 v2, s[46:47] offset:128
	v_mfma_f32_16x16x32_bf16 v[32:35], v[142:145], v[224:227], v[32:35]
	v_mfma_f32_16x16x32_bf16 v[28:31], v[150:153], v[224:227], v[28:31]
	v_mfma_f32_16x16x32_bf16 v[16:19], v[142:145], v[232:235], v[16:19]
	v_mfma_f32_16x16x32_bf16 v[12:15], v[150:153], v[232:235], v[12:15]
	v_mfma_f32_16x16x32_bf16 v[64:67], v[146:149], v[212:215], v[64:67]
	v_mfma_f32_16x16x32_bf16 v[60:63], v[154:157], v[212:215], v[60:63]
	v_mfma_f32_16x16x32_bf16 v[48:51], v[146:149], v[220:223], v[48:51]
	s_add_i32 m0, s61, 0xffffff80
	v_mfma_f32_16x16x32_bf16 v[44:47], v[154:157], v[220:223], v[44:47]
	global_load_lds_dwordx4 v132, s[46:47] offset:128
	v_mfma_f32_16x16x32_bf16 v[32:35], v[146:149], v[228:231], v[32:35]
	v_mfma_f32_16x16x32_bf16 v[28:31], v[154:157], v[228:231], v[28:31]
	v_mfma_f32_16x16x32_bf16 v[16:19], v[146:149], v[236:239], v[16:19]
	v_mfma_f32_16x16x32_bf16 v[12:15], v[154:157], v[236:239], v[12:15]
	v_mfma_f32_16x16x32_bf16 v[56:59], v[158:161], v[208:211], v[56:59]
	v_mfma_f32_16x16x32_bf16 v[52:55], v[180:183], v[208:211], v[52:55]
	v_mfma_f32_16x16x32_bf16 v[40:43], v[158:161], v[216:219], v[40:43]
	v_mfma_f32_16x16x32_bf16 v[36:39], v[180:183], v[216:219], v[36:39]
	v_mfma_f32_16x16x32_bf16 v[24:27], v[158:161], v[224:227], v[24:27]
	v_mfma_f32_16x16x32_bf16 v[20:23], v[180:183], v[224:227], v[20:23]
	v_mfma_f32_16x16x32_bf16 v[8:11], v[158:161], v[232:235], v[8:11]
	v_mfma_f32_16x16x32_bf16 v[4:7], v[180:183], v[232:235], v[4:7]
	v_mfma_f32_16x16x32_bf16 v[56:59], v[174:177], v[212:215], v[56:59]
	v_mfma_f32_16x16x32_bf16 v[52:55], v[204:207], v[212:215], v[52:55]
	v_mfma_f32_16x16x32_bf16 v[40:43], v[174:177], v[220:223], v[40:43]
	v_mfma_f32_16x16x32_bf16 v[36:39], v[204:207], v[220:223], v[36:39]
	v_mfma_f32_16x16x32_bf16 v[24:27], v[174:177], v[228:231], v[24:27]
	v_mfma_f32_16x16x32_bf16 v[20:23], v[204:207], v[228:231], v[20:23]
	v_mfma_f32_16x16x32_bf16 v[8:11], v[174:177], v[236:239], v[8:11]
	v_mfma_f32_16x16x32_bf16 v[4:7], v[204:207], v[236:239], v[4:7]
	s_setprio 3
	s_barrier
	s_add_i32 s31, s31, 2
	s_add_u32 s2, s2, 0x100
	s_addc_u32 s29, s29, 0
	s_cmp_gt_u32 s31, 29
	s_mov_b64 s[40:41], s[42:43]
	s_cbranch_scc0 .LBB0_2185
	s_and_b64 vcc, exec, s[26:27]
	s_cbranch_vccz .LBB0_2188
	s_barrier
